# balanced LDS-DMA staging in q/S5-in/GLU GEMM K-loops too; S5 stage 1 reads up front, stage 3 epilogue values prefetched
# speedup vs baseline: 1.0148x; 1.0014x over previous
.LBB0_781:
	s_or_b64 exec, exec, s[14:15]
	s_mul_i32 s2, s16, 0x1400000
	s_add_u32 s2, s94, s2
	s_addc_u32 s3, s95, 0
	s_lshl_b32 s14, s16, 22
	s_sub_u32 s14, 0, s14
	s_subb_u32 s15, 0, 0
	s_add_u32 s2, s2, s14
	s_addc_u32 s3, s3, s15
	s_add_u32 s2, s2, 0x13c00000
	s_addc_u32 s3, s3, 0
	v_ashrrev_i32_e32 v0, 6, v24
	s_lshl_b32 s14, s17, 13
	v_lshl_add_u32 v2, v0, 10, s14
	s_lshl_b32 s14, s88, 5
	s_and_b32 s55, s14, 0x60
	v_and_b32_e32 v146, 15, v24
	v_and_b32_e32 v1, 48, v24
	v_lshlrev_b32_e32 v3, 2, v24
	s_lshr_b32 s14, s55, 3
	v_lshl_or_b32 v1, v146, 6, v1
	v_and_b32_e32 v3, 32, v3
	v_add_lshl_u32 v0, v0, s14, 10
	v_bitop3_b32 v2, v1, v2, v3 bitop3:0xde
	v_bitop3_b32 v0, v1, v0, v3 bitop3:0xde
	v_lshlrev_b32_e32 v1, 15, v26
	v_and_b32_e32 v1, 0xffff0000, v1
	v_lshl_add_u32 v1, v27, 12, v1
	v_and_b32_e32 v3, 1, v26
	v_lshl_or_b32 v1, v3, 6, v1
	s_lshl_b32 s54, s17, 6
	v_lshl_add_u32 v136, v28, 1, v1
	v_lshlrev_b32_e32 v1, 15, v29
	s_cmpk_lt_u32 s33, 0x100
	v_and_b32_e32 v1, 0xffff0000, v1
	s_cselect_b64 s[14:15], -1, 0
	s_lshl_b32 s16, s17, 8
	v_lshl_add_u32 v1, v30, 12, v1
	v_and_b32_e32 v3, 1, v29
	s_add_i32 s57, s16, 0
	v_mov_b32_e32 v137, 0
	v_lshl_or_b32 v1, v3, 6, v1
	s_add_i32 s59, 0, 0x10000
	s_add_i32 s60, 0, 0x14000
	s_add_i32 s61, 0, 0x18000
	s_add_i32 s62, 0, 0x1c000
	s_mov_b32 s53, 0
	v_ashrrev_i32_e32 v147, 4, v24
	s_mov_b32 s56, 0x20000
	s_add_i32 s57, s57, 0x20000
	v_lshl_add_u32 v138, v31, 1, v1
	v_mov_b32_e32 v139, v137
	s_mov_b32 s58, 0x10000
	v_add_u32_e32 v148, s59, v0
	v_add_u32_e32 v149, s60, v0
	v_add_u32_e32 v150, 0, v2
	s_mov_b64 s[16:17], 0x80000
	v_add_u32_e32 v151, s61, v0
	v_add_u32_e32 v152, s62, v0
	s_mov_b32 s18, 0x3d8293ee
	s_mov_b64 s[20:21], 0x10000
	s_mov_b64 s[22:23], 0x20000
	s_mov_b64 s[24:25], 0x30000
	s_mov_b32 s63, 0x30000
	s_mov_b32 s64, 0x80000
	s_mov_b64 s[26:27], 0x90000
	s_mov_b32 s65, 0x90000
	s_mov_b64 s[28:29], 0xa0000
	s_mov_b32 s66, 0xa0000
	s_mov_b64 s[30:31], 0xb0000
	s_mov_b32 s67, 0xb0000
	s_waitcnt vmcnt(0)
	s_lshr_b32 s84, s88, 2
	s_mul_i32 s85, s84, 0x3000
	s_add_i32 s85, s85, s47
	s_mul_i32 s86, s84, 0x60000
	v_add_u32_e32 v222, s86, v136
	s_branch .LBB0_784

.LBB0_785:
	ds_read_b128 v[140:143], v148
	ds_read_b128 v[154:157], v148 offset:1024
	ds_read_b128 v[158:161], v148 offset:2048
	ds_read_b128 v[162:165], v148 offset:3072
	ds_read_b128 v[166:169], v149
	ds_read_b128 v[170:173], v149 offset:1024
	ds_read_b128 v[174:177], v149 offset:2048
	ds_read_b128 v[178:181], v149 offset:3072
	s_add_u32 s38, s36, 0xfff80080
	s_addc_u32 s39, s37, -1
	s_cmp_eq_u32 s75, 28
	s_cselect_b32 s41, s69, s39
	s_cselect_b32 s40, s70, s38
	s_cselect_b32 s39, s71, s74
	s_cselect_b32 s38, s72, s73
	s_sub_u32 s98, s36, 0x80000
	s_subb_u32 s99, s37, 0
	s_add_i32 m0, s85, 0x8000
	ds_read_b128 v[182:185], v150
	ds_read_b128 v[186:189], v150 offset:1024
	ds_read_b128 v[190:193], v150 offset:2048
	ds_read_b128 v[194:197], v150 offset:3072
	ds_read_b128 v[198:201], v150 offset:4096
	ds_read_b128 v[202:205], v150 offset:5120
	ds_read_b128 v[206:209], v150 offset:6144
	ds_read_b128 v[210:213], v150 offset:7168
	global_load_lds_dwordx4 v222, s[98:99]
	s_add_u32 s98, s98, 0x20000
	s_addc_u32 s99, s99, 0
	s_add_i32 m0, s85, 0x9000
	s_nop 0
	global_load_lds_dwordx4 v222, s[98:99]
	s_add_u32 s98, s98, 0x20000
	s_addc_u32 s99, s99, 0
	s_add_i32 m0, s85, 0xa000
	s_nop 0
	global_load_lds_dwordx4 v222, s[98:99]
	s_add_u32 s98, s98, 0x20000
	s_addc_u32 s99, s99, 0
	s_add_i32 m0, s85, 0xb000
	s_nop 0
	global_load_lds_dwordx4 v222, s[98:99]
	s_waitcnt vmcnt(8)
	s_waitcnt lgkmcnt(0)
	s_barrier
	s_setprio 1
	s_waitcnt lgkmcnt(0)
	v_mfma_f32_16x16x32_bf16 v[124:127], v[140:143], v[182:185], v[124:127]
	v_mfma_f32_16x16x32_bf16 v[120:123], v[158:161], v[182:185], v[120:123]
	v_mfma_f32_16x16x32_bf16 v[112:115], v[140:143], v[190:193], v[112:115]
	v_mfma_f32_16x16x32_bf16 v[104:107], v[158:161], v[190:193], v[104:107]
	v_mfma_f32_16x16x32_bf16 v[96:99], v[140:143], v[198:201], v[96:99]
	v_mfma_f32_16x16x32_bf16 v[88:91], v[158:161], v[198:201], v[88:91]
	v_mfma_f32_16x16x32_bf16 v[80:83], v[140:143], v[206:209], v[80:83]
	v_mfma_f32_16x16x32_bf16 v[72:75], v[158:161], v[206:209], v[72:75]
	v_mfma_f32_16x16x32_bf16 v[124:127], v[154:157], v[186:189], v[124:127]
	v_mfma_f32_16x16x32_bf16 v[120:123], v[162:165], v[186:189], v[120:123]
	v_mfma_f32_16x16x32_bf16 v[112:115], v[154:157], v[194:197], v[112:115]
	v_mfma_f32_16x16x32_bf16 v[104:107], v[162:165], v[194:197], v[104:107]
	v_mfma_f32_16x16x32_bf16 v[96:99], v[154:157], v[202:205], v[96:99]
	v_mfma_f32_16x16x32_bf16 v[88:91], v[162:165], v[202:205], v[88:91]
	v_mfma_f32_16x16x32_bf16 v[80:83], v[154:157], v[210:213], v[80:83]
	v_mfma_f32_16x16x32_bf16 v[72:75], v[162:165], v[210:213], v[72:75]
	s_setprio 0
	s_setprio 1
	v_mfma_f32_16x16x32_bf16 v[116:119], v[166:169], v[182:185], v[116:119]
	v_mfma_f32_16x16x32_bf16 v[108:111], v[174:177], v[182:185], v[108:111]
	v_mfma_f32_16x16x32_bf16 v[100:103], v[166:169], v[190:193], v[100:103]
	v_mfma_f32_16x16x32_bf16 v[92:95], v[174:177], v[190:193], v[92:95]
	v_mfma_f32_16x16x32_bf16 v[84:87], v[166:169], v[198:201], v[84:87]
	v_mfma_f32_16x16x32_bf16 v[76:79], v[174:177], v[198:201], v[76:79]
	v_mfma_f32_16x16x32_bf16 v[68:71], v[166:169], v[206:209], v[68:71]
	v_mfma_f32_16x16x32_bf16 v[64:67], v[174:177], v[206:209], v[64:67]
	v_mfma_f32_16x16x32_bf16 v[116:119], v[170:173], v[186:189], v[116:119]
	v_mfma_f32_16x16x32_bf16 v[108:111], v[178:181], v[186:189], v[108:111]
	v_mfma_f32_16x16x32_bf16 v[100:103], v[170:173], v[194:197], v[100:103]
	v_mfma_f32_16x16x32_bf16 v[92:95], v[178:181], v[194:197], v[92:95]
	v_mfma_f32_16x16x32_bf16 v[84:87], v[170:173], v[202:205], v[84:87]
	v_mfma_f32_16x16x32_bf16 v[76:79], v[178:181], v[202:205], v[76:79]
	v_mfma_f32_16x16x32_bf16 v[68:71], v[170:173], v[210:213], v[68:71]
	v_mfma_f32_16x16x32_bf16 v[64:67], v[178:181], v[210:213], v[64:67]
	s_setprio 0
	s_barrier
	s_add_i32 s76, s59, s5
	v_lshl_add_u64 v[144:145], s[38:39], 0, v[130:131]
	s_mov_b32 m0, s76
	ds_read_b128 v[182:185], v150 offset:16384
	ds_read_b128 v[186:189], v150 offset:17408
	ds_read_b128 v[190:193], v150 offset:18432
	ds_read_b128 v[194:197], v150 offset:19456
	ds_read_b128 v[198:201], v150 offset:20480
	ds_read_b128 v[202:205], v150 offset:21504
	ds_read_b128 v[206:209], v150 offset:22528
	ds_read_b128 v[210:213], v150 offset:23552
	global_load_lds_dwordx4 v[144:145], off
	s_add_i32 m0, s76, 0x2000
	s_add_u32 s76, s38, 0x80000
	v_lshl_add_u64 v[214:215], s[38:39], 0, v[134:135]
	s_addc_u32 s77, s39, 0
	s_add_i32 s78, s60, s5
	global_load_lds_dwordx4 v[214:215], off
	v_lshl_add_u64 v[216:217], s[76:77], 0, v[130:131]
	s_mov_b32 m0, s78
	global_load_lds_dwordx4 v[216:217], off
	v_lshl_add_u64 v[216:217], s[76:77], 0, v[134:135]
	s_add_i32 m0, s78, 0x2000
	s_nop 0
	global_load_lds_dwordx4 v[216:217], off
	s_waitcnt vmcnt(8)
	s_waitcnt lgkmcnt(0)
	s_barrier
	s_setprio 1
	s_waitcnt lgkmcnt(0)
	v_mfma_f32_16x16x32_bf16 v[60:63], v[140:143], v[182:185], v[60:63]
	v_mfma_f32_16x16x32_bf16 v[56:59], v[158:161], v[182:185], v[56:59]
	v_mfma_f32_16x16x32_bf16 v[48:51], v[140:143], v[190:193], v[48:51]
	v_mfma_f32_16x16x32_bf16 v[40:43], v[158:161], v[190:193], v[40:43]
	v_mfma_f32_16x16x32_bf16 v[32:35], v[140:143], v[198:201], v[32:35]
	v_mfma_f32_16x16x32_bf16 v[24:27], v[158:161], v[198:201], v[24:27]
	v_mfma_f32_16x16x32_bf16 v[16:19], v[140:143], v[206:209], v[16:19]
	v_mfma_f32_16x16x32_bf16 v[8:11], v[158:161], v[206:209], v[8:11]
	v_mfma_f32_16x16x32_bf16 v[60:63], v[154:157], v[186:189], v[60:63]
	v_mfma_f32_16x16x32_bf16 v[56:59], v[162:165], v[186:189], v[56:59]
	v_mfma_f32_16x16x32_bf16 v[48:51], v[154:157], v[194:197], v[48:51]
	v_mfma_f32_16x16x32_bf16 v[40:43], v[162:165], v[194:197], v[40:43]
	v_mfma_f32_16x16x32_bf16 v[32:35], v[154:157], v[202:205], v[32:35]
	v_mfma_f32_16x16x32_bf16 v[24:27], v[162:165], v[202:205], v[24:27]
	v_mfma_f32_16x16x32_bf16 v[16:19], v[154:157], v[210:213], v[16:19]
	v_mfma_f32_16x16x32_bf16 v[8:11], v[162:165], v[210:213], v[8:11]
	s_setprio 0
	s_setprio 1
	v_mfma_f32_16x16x32_bf16 v[52:55], v[166:169], v[182:185], v[52:55]
	v_mfma_f32_16x16x32_bf16 v[44:47], v[174:177], v[182:185], v[44:47]
	v_mfma_f32_16x16x32_bf16 v[36:39], v[166:169], v[190:193], v[36:39]
	v_mfma_f32_16x16x32_bf16 v[28:31], v[174:177], v[190:193], v[28:31]
	v_mfma_f32_16x16x32_bf16 v[20:23], v[166:169], v[198:201], v[20:23]
	v_mfma_f32_16x16x32_bf16 v[12:15], v[174:177], v[198:201], v[12:15]
	v_mfma_f32_16x16x32_bf16 v[4:7], v[166:169], v[206:209], v[4:7]
	v_mfma_f32_16x16x32_bf16 v[0:3], v[174:177], v[206:209], v[0:3]
	v_mfma_f32_16x16x32_bf16 v[52:55], v[170:173], v[186:189], v[52:55]
	v_mfma_f32_16x16x32_bf16 v[44:47], v[178:181], v[186:189], v[44:47]
	v_mfma_f32_16x16x32_bf16 v[36:39], v[170:173], v[194:197], v[36:39]
	v_mfma_f32_16x16x32_bf16 v[28:31], v[178:181], v[194:197], v[28:31]
	v_mfma_f32_16x16x32_bf16 v[20:23], v[170:173], v[202:205], v[20:23]
	v_mfma_f32_16x16x32_bf16 v[12:15], v[178:181], v[202:205], v[12:15]
	v_mfma_f32_16x16x32_bf16 v[4:7], v[170:173], v[210:213], v[4:7]
	v_mfma_f32_16x16x32_bf16 v[0:3], v[178:181], v[210:213], v[0:3]
	s_setprio 0
	s_waitcnt vmcnt(4)
	s_barrier
	ds_read_b128 v[140:143], v151
	ds_read_b128 v[154:157], v151 offset:1024
	ds_read_b128 v[158:161], v151 offset:2048
	ds_read_b128 v[162:165], v151 offset:3072
	ds_read_b128 v[166:169], v152
	ds_read_b128 v[170:173], v152 offset:1024
	ds_read_b128 v[174:177], v152 offset:2048
	ds_read_b128 v[178:181], v152 offset:3072
	s_mov_b32 s98, s40
	s_mov_b32 s99, s41
	s_add_i32 m0, s85, 0
	ds_read_b128 v[182:185], v150 offset:32768
	ds_read_b128 v[186:189], v150 offset:33792
	ds_read_b128 v[190:193], v150 offset:34816
	ds_read_b128 v[194:197], v150 offset:35840
	ds_read_b128 v[198:201], v150 offset:36864
	ds_read_b128 v[202:205], v150 offset:37888
	ds_read_b128 v[206:209], v150 offset:38912
	ds_read_b128 v[210:213], v150 offset:39936
	global_load_lds_dwordx4 v222, s[98:99]
	s_add_u32 s98, s98, 0x20000
	s_addc_u32 s99, s99, 0
	s_add_i32 m0, s85, 0x1000
	s_nop 0
	global_load_lds_dwordx4 v222, s[98:99]
	s_add_u32 s98, s98, 0x20000
	s_addc_u32 s99, s99, 0
	s_add_i32 m0, s85, 0x2000
	s_nop 0
	global_load_lds_dwordx4 v222, s[98:99]
	s_add_u32 s98, s98, 0x20000
	s_addc_u32 s99, s99, 0
	s_add_i32 m0, s85, 0x3000
	s_nop 0
	global_load_lds_dwordx4 v222, s[98:99]
	s_waitcnt vmcnt(8)
	s_waitcnt lgkmcnt(0)
	s_barrier
	s_setprio 1
	s_waitcnt lgkmcnt(0)
	v_mfma_f32_16x16x32_bf16 v[124:127], v[140:143], v[182:185], v[124:127]
	v_mfma_f32_16x16x32_bf16 v[120:123], v[158:161], v[182:185], v[120:123]
	v_mfma_f32_16x16x32_bf16 v[112:115], v[140:143], v[190:193], v[112:115]
	v_mfma_f32_16x16x32_bf16 v[104:107], v[158:161], v[190:193], v[104:107]
	v_mfma_f32_16x16x32_bf16 v[96:99], v[140:143], v[198:201], v[96:99]
	v_mfma_f32_16x16x32_bf16 v[88:91], v[158:161], v[198:201], v[88:91]
	v_mfma_f32_16x16x32_bf16 v[80:83], v[140:143], v[206:209], v[80:83]
	v_mfma_f32_16x16x32_bf16 v[72:75], v[158:161], v[206:209], v[72:75]
	v_mfma_f32_16x16x32_bf16 v[124:127], v[154:157], v[186:189], v[124:127]
	v_mfma_f32_16x16x32_bf16 v[120:123], v[162:165], v[186:189], v[120:123]
	v_mfma_f32_16x16x32_bf16 v[112:115], v[154:157], v[194:197], v[112:115]
	v_mfma_f32_16x16x32_bf16 v[104:107], v[162:165], v[194:197], v[104:107]
	v_mfma_f32_16x16x32_bf16 v[96:99], v[154:157], v[202:205], v[96:99]
	v_mfma_f32_16x16x32_bf16 v[88:91], v[162:165], v[202:205], v[88:91]
	v_mfma_f32_16x16x32_bf16 v[80:83], v[154:157], v[210:213], v[80:83]
	v_mfma_f32_16x16x32_bf16 v[72:75], v[162:165], v[210:213], v[72:75]
	s_setprio 0
	s_setprio 1
	v_mfma_f32_16x16x32_bf16 v[116:119], v[166:169], v[182:185], v[116:119]
	v_mfma_f32_16x16x32_bf16 v[108:111], v[174:177], v[182:185], v[108:111]
	v_mfma_f32_16x16x32_bf16 v[100:103], v[166:169], v[190:193], v[100:103]
	v_mfma_f32_16x16x32_bf16 v[92:95], v[174:177], v[190:193], v[92:95]
	v_mfma_f32_16x16x32_bf16 v[84:87], v[166:169], v[198:201], v[84:87]
	v_mfma_f32_16x16x32_bf16 v[76:79], v[174:177], v[198:201], v[76:79]
	v_mfma_f32_16x16x32_bf16 v[68:71], v[166:169], v[206:209], v[68:71]
	v_mfma_f32_16x16x32_bf16 v[64:67], v[174:177], v[206:209], v[64:67]
	v_mfma_f32_16x16x32_bf16 v[116:119], v[170:173], v[186:189], v[116:119]
	v_mfma_f32_16x16x32_bf16 v[108:111], v[178:181], v[186:189], v[108:111]
	v_mfma_f32_16x16x32_bf16 v[100:103], v[170:173], v[194:197], v[100:103]
	v_mfma_f32_16x16x32_bf16 v[92:95], v[178:181], v[194:197], v[92:95]
	v_mfma_f32_16x16x32_bf16 v[84:87], v[170:173], v[202:205], v[84:87]
	v_mfma_f32_16x16x32_bf16 v[76:79], v[178:181], v[202:205], v[76:79]
	v_mfma_f32_16x16x32_bf16 v[68:71], v[170:173], v[210:213], v[68:71]
	v_mfma_f32_16x16x32_bf16 v[64:67], v[178:181], v[210:213], v[64:67]
	s_setprio 0
	s_barrier
	s_add_i32 s40, s61, s5
	v_lshl_add_u64 v[144:145], v[144:145], 0, s[12:13]
	s_mov_b32 m0, s40
	ds_read_b128 v[182:185], v150 offset:49152
	ds_read_b128 v[186:189], v150 offset:50176
	ds_read_b128 v[190:193], v150 offset:51200
	ds_read_b128 v[194:197], v150 offset:52224
	ds_read_b128 v[198:201], v150 offset:53248
	ds_read_b128 v[202:205], v150 offset:54272
	ds_read_b128 v[206:209], v150 offset:55296
	ds_read_b128 v[210:213], v150 offset:56320
	global_load_lds_dwordx4 v[144:145], off
	s_add_i32 m0, s40, 0x2000
	s_add_u32 s38, s38, 0x80080
	v_lshl_add_u64 v[144:145], v[214:215], 0, s[12:13]
	s_addc_u32 s39, s39, 0
	s_add_i32 s40, s62, s5
	global_load_lds_dwordx4 v[144:145], off
	v_lshl_add_u64 v[144:145], s[38:39], 0, v[130:131]
	s_mov_b32 m0, s40
	s_nop 0
	global_load_lds_dwordx4 v[144:145], off
	v_lshl_add_u64 v[144:145], s[38:39], 0, v[134:135]
	s_add_i32 m0, s40, 0x2000
	s_nop 0
	global_load_lds_dwordx4 v[144:145], off
	s_waitcnt vmcnt(8)
	s_waitcnt lgkmcnt(0)
	s_barrier
	s_setprio 1
	s_waitcnt lgkmcnt(0)
	v_mfma_f32_16x16x32_bf16 v[60:63], v[140:143], v[182:185], v[60:63]
	v_mfma_f32_16x16x32_bf16 v[56:59], v[158:161], v[182:185], v[56:59]
	v_mfma_f32_16x16x32_bf16 v[48:51], v[140:143], v[190:193], v[48:51]
	v_mfma_f32_16x16x32_bf16 v[40:43], v[158:161], v[190:193], v[40:43]
	v_mfma_f32_16x16x32_bf16 v[32:35], v[140:143], v[198:201], v[32:35]
	v_mfma_f32_16x16x32_bf16 v[24:27], v[158:161], v[198:201], v[24:27]
	v_mfma_f32_16x16x32_bf16 v[16:19], v[140:143], v[206:209], v[16:19]
	v_mfma_f32_16x16x32_bf16 v[8:11], v[158:161], v[206:209], v[8:11]
	v_mfma_f32_16x16x32_bf16 v[60:63], v[154:157], v[186:189], v[60:63]
	v_mfma_f32_16x16x32_bf16 v[56:59], v[162:165], v[186:189], v[56:59]
	v_mfma_f32_16x16x32_bf16 v[48:51], v[154:157], v[194:197], v[48:51]
	v_mfma_f32_16x16x32_bf16 v[40:43], v[162:165], v[194:197], v[40:43]
	v_mfma_f32_16x16x32_bf16 v[32:35], v[154:157], v[202:205], v[32:35]
	v_mfma_f32_16x16x32_bf16 v[24:27], v[162:165], v[202:205], v[24:27]
	v_mfma_f32_16x16x32_bf16 v[16:19], v[154:157], v[210:213], v[16:19]
	v_mfma_f32_16x16x32_bf16 v[8:11], v[162:165], v[210:213], v[8:11]
	s_setprio 0
	s_setprio 1
	v_mfma_f32_16x16x32_bf16 v[52:55], v[166:169], v[182:185], v[52:55]
	v_mfma_f32_16x16x32_bf16 v[44:47], v[174:177], v[182:185], v[44:47]
	v_mfma_f32_16x16x32_bf16 v[36:39], v[166:169], v[190:193], v[36:39]
	v_mfma_f32_16x16x32_bf16 v[28:31], v[174:177], v[190:193], v[28:31]
	v_mfma_f32_16x16x32_bf16 v[20:23], v[166:169], v[198:201], v[20:23]
	v_mfma_f32_16x16x32_bf16 v[12:15], v[174:177], v[198:201], v[12:15]
	v_mfma_f32_16x16x32_bf16 v[4:7], v[166:169], v[206:209], v[4:7]
	v_mfma_f32_16x16x32_bf16 v[0:3], v[174:177], v[206:209], v[0:3]
	v_mfma_f32_16x16x32_bf16 v[52:55], v[170:173], v[186:189], v[52:55]
	v_mfma_f32_16x16x32_bf16 v[44:47], v[178:181], v[186:189], v[44:47]
	v_mfma_f32_16x16x32_bf16 v[36:39], v[170:173], v[194:197], v[36:39]
	v_mfma_f32_16x16x32_bf16 v[28:31], v[178:181], v[194:197], v[28:31]
	v_mfma_f32_16x16x32_bf16 v[20:23], v[170:173], v[202:205], v[20:23]
	v_mfma_f32_16x16x32_bf16 v[12:15], v[178:181], v[202:205], v[12:15]
	v_mfma_f32_16x16x32_bf16 v[4:7], v[170:173], v[210:213], v[4:7]
	v_mfma_f32_16x16x32_bf16 v[0:3], v[178:181], v[210:213], v[0:3]
	s_setprio 0
	s_waitcnt vmcnt(4)
	s_barrier
	s_add_i32 s75, s75, 2
	s_add_u32 s36, s36, 0x100
	s_addc_u32 s37, s37, 0
	s_add_u32 s73, s73, 0x100
	s_addc_u32 s74, s74, 0
	s_cmp_gt_u32 s75, 29
	s_cbranch_scc0 .LBB0_785
	s_and_b64 vcc, exec, s[14:15]
	s_cbranch_vccz .LBB0_788
	s_barrier

.LBB0_1320:
	s_or_b64 exec, exec, s[12:13]
	s_mul_i32 s2, s14, 0x1400000
	s_add_u32 s2, s94, s2
	s_addc_u32 s3, s95, 0
	s_lshl_b32 s12, s14, 22
	s_sub_u32 s12, 0, s12
	s_subb_u32 s13, 0, 0
	s_add_u32 s2, s2, s12
	s_addc_u32 s3, s3, s13
	s_add_u32 s2, s2, 0x14000000
	s_addc_u32 s3, s3, 0
	v_ashrrev_i32_e32 v0, 6, v24
	s_lshl_b32 s12, s15, 13
	v_lshl_add_u32 v2, v0, 10, s12
	s_lshl_b32 s12, s88, 5
	s_and_b32 s52, s12, 0x60
	v_and_b32_e32 v146, 15, v24
	v_and_b32_e32 v1, 48, v24
	v_lshlrev_b32_e32 v3, 2, v24
	s_lshr_b32 s12, s52, 3
	v_lshl_or_b32 v1, v146, 6, v1
	v_and_b32_e32 v3, 32, v3
	v_add_lshl_u32 v0, v0, s12, 10
	v_bitop3_b32 v2, v1, v2, v3 bitop3:0xde
	v_bitop3_b32 v0, v1, v0, v3 bitop3:0xde
	v_lshlrev_b32_e32 v1, 15, v26
	v_and_b32_e32 v1, 0xffff0000, v1
	v_lshl_add_u32 v1, v27, 12, v1
	v_and_b32_e32 v3, 1, v26
	v_lshl_or_b32 v1, v3, 6, v1
	s_lshl_b32 s51, s15, 6
	v_lshl_add_u32 v136, v28, 1, v1
	v_lshlrev_b32_e32 v1, 15, v29
	s_cmpk_lt_u32 s33, 0x100
	v_and_b32_e32 v1, 0xffff0000, v1
	s_cselect_b64 s[12:13], -1, 0
	s_lshl_b32 s14, s15, 8
	v_lshl_add_u32 v1, v30, 12, v1
	v_and_b32_e32 v3, 1, v29
	s_add_i32 s54, s14, 0
	v_mov_b32_e32 v137, 0
	v_lshl_or_b32 v1, v3, 6, v1
	s_add_i32 s56, 0, 0x10000
	s_add_i32 s57, 0, 0x14000
	s_add_i32 s58, 0, 0x18000
	s_add_i32 s59, 0, 0x1c000
	s_mov_b32 s50, 0
	v_ashrrev_i32_e32 v147, 4, v24
	s_mov_b32 s53, 0x20000
	s_add_i32 s54, s54, 0x20000
	v_lshl_add_u32 v138, v31, 1, v1
	v_mov_b32_e32 v139, v137
	s_mov_b32 s55, 0x10000
	v_add_u32_e32 v148, s56, v0
	v_add_u32_e32 v149, s57, v0
	v_add_u32_e32 v150, 0, v2
	s_mov_b64 s[14:15], 0x80000
	v_add_u32_e32 v151, s58, v0
	v_add_u32_e32 v152, s59, v0
	s_mov_b64 s[16:17], 0x10000
	s_mov_b64 s[18:19], 0x20000
	s_mov_b64 s[20:21], 0x30000
	s_mov_b32 s60, 0x30000
	s_mov_b32 s61, 0x80000
	s_mov_b64 s[22:23], 0x90000
	s_mov_b32 s62, 0x90000
	s_mov_b64 s[24:25], 0xa0000
	s_mov_b32 s63, 0xa0000
	s_mov_b64 s[26:27], 0xb0000
	s_mov_b32 s64, 0xb0000
	s_lshr_b32 s84, s88, 2
	s_mul_i32 s85, s84, 0x3000
	s_add_i32 s85, s85, s44
	s_mul_i32 s86, s84, 0x60000
	v_add_u32_e32 v222, s86, v136
	s_branch .LBB0_1323

.LBB0_1324:
	ds_read_b128 v[140:143], v148
	ds_read_b128 v[154:157], v148 offset:1024
	ds_read_b128 v[158:161], v148 offset:2048
	ds_read_b128 v[162:165], v148 offset:3072
	ds_read_b128 v[166:169], v149
	ds_read_b128 v[170:173], v149 offset:1024
	ds_read_b128 v[174:177], v149 offset:2048
	ds_read_b128 v[178:181], v149 offset:3072
	s_add_u32 s34, s30, 0xfff80080
	s_addc_u32 s35, s31, -1
	s_cmp_eq_u32 s72, 28
	s_cselect_b32 s37, s66, s35
	s_cselect_b32 s36, s67, s34
	s_cselect_b32 s35, s68, s71
	s_cselect_b32 s34, s69, s70
	s_sub_u32 s98, s30, 0x80000
	s_subb_u32 s99, s31, 0
	s_add_i32 m0, s85, 0x8000
	ds_read_b128 v[182:185], v150
	ds_read_b128 v[186:189], v150 offset:1024
	ds_read_b128 v[190:193], v150 offset:2048
	ds_read_b128 v[194:197], v150 offset:3072
	ds_read_b128 v[198:201], v150 offset:4096
	ds_read_b128 v[202:205], v150 offset:5120
	ds_read_b128 v[206:209], v150 offset:6144
	ds_read_b128 v[210:213], v150 offset:7168
	global_load_lds_dwordx4 v222, s[98:99]
	s_add_u32 s98, s98, 0x20000
	s_addc_u32 s99, s99, 0
	s_add_i32 m0, s85, 0x9000
	s_nop 0
	global_load_lds_dwordx4 v222, s[98:99]
	s_add_u32 s98, s98, 0x20000
	s_addc_u32 s99, s99, 0
	s_add_i32 m0, s85, 0xa000
	s_nop 0
	global_load_lds_dwordx4 v222, s[98:99]
	s_add_u32 s98, s98, 0x20000
	s_addc_u32 s99, s99, 0
	s_add_i32 m0, s85, 0xb000
	s_nop 0
	global_load_lds_dwordx4 v222, s[98:99]
	s_waitcnt vmcnt(8)
	s_waitcnt lgkmcnt(0)
	s_barrier
	s_setprio 1
	s_waitcnt lgkmcnt(0)
	v_mfma_f32_16x16x32_bf16 v[124:127], v[140:143], v[182:185], v[124:127]
	v_mfma_f32_16x16x32_bf16 v[120:123], v[158:161], v[182:185], v[120:123]
	v_mfma_f32_16x16x32_bf16 v[112:115], v[140:143], v[190:193], v[112:115]
	v_mfma_f32_16x16x32_bf16 v[104:107], v[158:161], v[190:193], v[104:107]
	v_mfma_f32_16x16x32_bf16 v[96:99], v[140:143], v[198:201], v[96:99]
	v_mfma_f32_16x16x32_bf16 v[88:91], v[158:161], v[198:201], v[88:91]
	v_mfma_f32_16x16x32_bf16 v[80:83], v[140:143], v[206:209], v[80:83]
	v_mfma_f32_16x16x32_bf16 v[72:75], v[158:161], v[206:209], v[72:75]
	v_mfma_f32_16x16x32_bf16 v[124:127], v[154:157], v[186:189], v[124:127]
	v_mfma_f32_16x16x32_bf16 v[120:123], v[162:165], v[186:189], v[120:123]
	v_mfma_f32_16x16x32_bf16 v[112:115], v[154:157], v[194:197], v[112:115]
	v_mfma_f32_16x16x32_bf16 v[104:107], v[162:165], v[194:197], v[104:107]
	v_mfma_f32_16x16x32_bf16 v[96:99], v[154:157], v[202:205], v[96:99]
	v_mfma_f32_16x16x32_bf16 v[88:91], v[162:165], v[202:205], v[88:91]
	v_mfma_f32_16x16x32_bf16 v[80:83], v[154:157], v[210:213], v[80:83]
	v_mfma_f32_16x16x32_bf16 v[72:75], v[162:165], v[210:213], v[72:75]
	s_setprio 0
	s_setprio 1
	v_mfma_f32_16x16x32_bf16 v[116:119], v[166:169], v[182:185], v[116:119]
	v_mfma_f32_16x16x32_bf16 v[108:111], v[174:177], v[182:185], v[108:111]
	v_mfma_f32_16x16x32_bf16 v[100:103], v[166:169], v[190:193], v[100:103]
	v_mfma_f32_16x16x32_bf16 v[92:95], v[174:177], v[190:193], v[92:95]
	v_mfma_f32_16x16x32_bf16 v[84:87], v[166:169], v[198:201], v[84:87]
	v_mfma_f32_16x16x32_bf16 v[76:79], v[174:177], v[198:201], v[76:79]
	v_mfma_f32_16x16x32_bf16 v[68:71], v[166:169], v[206:209], v[68:71]
	v_mfma_f32_16x16x32_bf16 v[64:67], v[174:177], v[206:209], v[64:67]
	v_mfma_f32_16x16x32_bf16 v[116:119], v[170:173], v[186:189], v[116:119]
	v_mfma_f32_16x16x32_bf16 v[108:111], v[178:181], v[186:189], v[108:111]
	v_mfma_f32_16x16x32_bf16 v[100:103], v[170:173], v[194:197], v[100:103]
	v_mfma_f32_16x16x32_bf16 v[92:95], v[178:181], v[194:197], v[92:95]
	v_mfma_f32_16x16x32_bf16 v[84:87], v[170:173], v[202:205], v[84:87]
	v_mfma_f32_16x16x32_bf16 v[76:79], v[178:181], v[202:205], v[76:79]
	v_mfma_f32_16x16x32_bf16 v[68:71], v[170:173], v[210:213], v[68:71]
	v_mfma_f32_16x16x32_bf16 v[64:67], v[178:181], v[210:213], v[64:67]
	s_setprio 0
	s_barrier
	s_add_i32 s73, s56, s5
	v_lshl_add_u64 v[144:145], s[34:35], 0, v[130:131]
	s_mov_b32 m0, s73
	ds_read_b128 v[182:185], v150 offset:16384
	ds_read_b128 v[186:189], v150 offset:17408
	ds_read_b128 v[190:193], v150 offset:18432
	ds_read_b128 v[194:197], v150 offset:19456
	ds_read_b128 v[198:201], v150 offset:20480
	ds_read_b128 v[202:205], v150 offset:21504
	ds_read_b128 v[206:209], v150 offset:22528
	ds_read_b128 v[210:213], v150 offset:23552
	global_load_lds_dwordx4 v[144:145], off
	s_add_i32 m0, s73, 0x2000
	s_add_u32 s74, s34, 0x80000
	v_lshl_add_u64 v[214:215], s[34:35], 0, v[134:135]
	s_addc_u32 s75, s35, 0
	s_add_i32 s73, s57, s5
	global_load_lds_dwordx4 v[214:215], off
	v_lshl_add_u64 v[216:217], s[74:75], 0, v[130:131]
	s_mov_b32 m0, s73
	global_load_lds_dwordx4 v[216:217], off
	v_lshl_add_u64 v[216:217], s[74:75], 0, v[134:135]
	s_add_i32 m0, s73, 0x2000
	s_nop 0
	global_load_lds_dwordx4 v[216:217], off
	s_waitcnt vmcnt(8)
	s_waitcnt lgkmcnt(0)
	s_barrier
	s_setprio 1
	s_waitcnt lgkmcnt(0)
	v_mfma_f32_16x16x32_bf16 v[60:63], v[140:143], v[182:185], v[60:63]
	v_mfma_f32_16x16x32_bf16 v[56:59], v[158:161], v[182:185], v[56:59]
	v_mfma_f32_16x16x32_bf16 v[48:51], v[140:143], v[190:193], v[48:51]
	v_mfma_f32_16x16x32_bf16 v[40:43], v[158:161], v[190:193], v[40:43]
	v_mfma_f32_16x16x32_bf16 v[32:35], v[140:143], v[198:201], v[32:35]
	v_mfma_f32_16x16x32_bf16 v[24:27], v[158:161], v[198:201], v[24:27]
	v_mfma_f32_16x16x32_bf16 v[16:19], v[140:143], v[206:209], v[16:19]
	v_mfma_f32_16x16x32_bf16 v[8:11], v[158:161], v[206:209], v[8:11]
	v_mfma_f32_16x16x32_bf16 v[60:63], v[154:157], v[186:189], v[60:63]
	v_mfma_f32_16x16x32_bf16 v[56:59], v[162:165], v[186:189], v[56:59]
	v_mfma_f32_16x16x32_bf16 v[48:51], v[154:157], v[194:197], v[48:51]
	v_mfma_f32_16x16x32_bf16 v[40:43], v[162:165], v[194:197], v[40:43]
	v_mfma_f32_16x16x32_bf16 v[32:35], v[154:157], v[202:205], v[32:35]
	v_mfma_f32_16x16x32_bf16 v[24:27], v[162:165], v[202:205], v[24:27]
	v_mfma_f32_16x16x32_bf16 v[16:19], v[154:157], v[210:213], v[16:19]
	v_mfma_f32_16x16x32_bf16 v[8:11], v[162:165], v[210:213], v[8:11]
	s_setprio 0
	s_setprio 1
	v_mfma_f32_16x16x32_bf16 v[52:55], v[166:169], v[182:185], v[52:55]
	v_mfma_f32_16x16x32_bf16 v[44:47], v[174:177], v[182:185], v[44:47]
	v_mfma_f32_16x16x32_bf16 v[36:39], v[166:169], v[190:193], v[36:39]
	v_mfma_f32_16x16x32_bf16 v[28:31], v[174:177], v[190:193], v[28:31]
	v_mfma_f32_16x16x32_bf16 v[20:23], v[166:169], v[198:201], v[20:23]
	v_mfma_f32_16x16x32_bf16 v[12:15], v[174:177], v[198:201], v[12:15]
	v_mfma_f32_16x16x32_bf16 v[4:7], v[166:169], v[206:209], v[4:7]
	v_mfma_f32_16x16x32_bf16 v[0:3], v[174:177], v[206:209], v[0:3]
	v_mfma_f32_16x16x32_bf16 v[52:55], v[170:173], v[186:189], v[52:55]
	v_mfma_f32_16x16x32_bf16 v[44:47], v[178:181], v[186:189], v[44:47]
	v_mfma_f32_16x16x32_bf16 v[36:39], v[170:173], v[194:197], v[36:39]
	v_mfma_f32_16x16x32_bf16 v[28:31], v[178:181], v[194:197], v[28:31]
	v_mfma_f32_16x16x32_bf16 v[20:23], v[170:173], v[202:205], v[20:23]
	v_mfma_f32_16x16x32_bf16 v[12:15], v[178:181], v[202:205], v[12:15]
	v_mfma_f32_16x16x32_bf16 v[4:7], v[170:173], v[210:213], v[4:7]
	v_mfma_f32_16x16x32_bf16 v[0:3], v[178:181], v[210:213], v[0:3]
	s_setprio 0
	s_waitcnt vmcnt(4)
	s_barrier
	ds_read_b128 v[140:143], v151
	ds_read_b128 v[154:157], v151 offset:1024
	ds_read_b128 v[158:161], v151 offset:2048
	ds_read_b128 v[162:165], v151 offset:3072
	ds_read_b128 v[166:169], v152
	ds_read_b128 v[170:173], v152 offset:1024
	ds_read_b128 v[174:177], v152 offset:2048
	ds_read_b128 v[178:181], v152 offset:3072
	s_mov_b32 s98, s36
	s_mov_b32 s99, s37
	s_add_i32 m0, s85, 0
	ds_read_b128 v[182:185], v150 offset:32768
	ds_read_b128 v[186:189], v150 offset:33792
	ds_read_b128 v[190:193], v150 offset:34816
	ds_read_b128 v[194:197], v150 offset:35840
	ds_read_b128 v[198:201], v150 offset:36864
	ds_read_b128 v[202:205], v150 offset:37888
	ds_read_b128 v[206:209], v150 offset:38912
	ds_read_b128 v[210:213], v150 offset:39936
	global_load_lds_dwordx4 v222, s[98:99]
	s_add_u32 s98, s98, 0x20000
	s_addc_u32 s99, s99, 0
	s_add_i32 m0, s85, 0x1000
	s_nop 0
	global_load_lds_dwordx4 v222, s[98:99]
	s_add_u32 s98, s98, 0x20000
	s_addc_u32 s99, s99, 0
	s_add_i32 m0, s85, 0x2000
	s_nop 0
	global_load_lds_dwordx4 v222, s[98:99]
	s_add_u32 s98, s98, 0x20000
	s_addc_u32 s99, s99, 0
	s_add_i32 m0, s85, 0x3000
	s_nop 0
	global_load_lds_dwordx4 v222, s[98:99]
	s_waitcnt vmcnt(8)
	s_waitcnt lgkmcnt(0)
	s_barrier
	s_setprio 1
	s_waitcnt lgkmcnt(0)
	v_mfma_f32_16x16x32_bf16 v[124:127], v[140:143], v[182:185], v[124:127]
	v_mfma_f32_16x16x32_bf16 v[120:123], v[158:161], v[182:185], v[120:123]
	v_mfma_f32_16x16x32_bf16 v[112:115], v[140:143], v[190:193], v[112:115]
	v_mfma_f32_16x16x32_bf16 v[104:107], v[158:161], v[190:193], v[104:107]
	v_mfma_f32_16x16x32_bf16 v[96:99], v[140:143], v[198:201], v[96:99]
	v_mfma_f32_16x16x32_bf16 v[88:91], v[158:161], v[198:201], v[88:91]
	v_mfma_f32_16x16x32_bf16 v[80:83], v[140:143], v[206:209], v[80:83]
	v_mfma_f32_16x16x32_bf16 v[72:75], v[158:161], v[206:209], v[72:75]
	v_mfma_f32_16x16x32_bf16 v[124:127], v[154:157], v[186:189], v[124:127]
	v_mfma_f32_16x16x32_bf16 v[120:123], v[162:165], v[186:189], v[120:123]
	v_mfma_f32_16x16x32_bf16 v[112:115], v[154:157], v[194:197], v[112:115]
	v_mfma_f32_16x16x32_bf16 v[104:107], v[162:165], v[194:197], v[104:107]
	v_mfma_f32_16x16x32_bf16 v[96:99], v[154:157], v[202:205], v[96:99]
	v_mfma_f32_16x16x32_bf16 v[88:91], v[162:165], v[202:205], v[88:91]
	v_mfma_f32_16x16x32_bf16 v[80:83], v[154:157], v[210:213], v[80:83]
	v_mfma_f32_16x16x32_bf16 v[72:75], v[162:165], v[210:213], v[72:75]
	s_setprio 0
	s_setprio 1
	v_mfma_f32_16x16x32_bf16 v[116:119], v[166:169], v[182:185], v[116:119]
	v_mfma_f32_16x16x32_bf16 v[108:111], v[174:177], v[182:185], v[108:111]
	v_mfma_f32_16x16x32_bf16 v[100:103], v[166:169], v[190:193], v[100:103]
	v_mfma_f32_16x16x32_bf16 v[92:95], v[174:177], v[190:193], v[92:95]
	v_mfma_f32_16x16x32_bf16 v[84:87], v[166:169], v[198:201], v[84:87]
	v_mfma_f32_16x16x32_bf16 v[76:79], v[174:177], v[198:201], v[76:79]
	v_mfma_f32_16x16x32_bf16 v[68:71], v[166:169], v[206:209], v[68:71]
	v_mfma_f32_16x16x32_bf16 v[64:67], v[174:177], v[206:209], v[64:67]
	v_mfma_f32_16x16x32_bf16 v[116:119], v[170:173], v[186:189], v[116:119]
	v_mfma_f32_16x16x32_bf16 v[108:111], v[178:181], v[186:189], v[108:111]
	v_mfma_f32_16x16x32_bf16 v[100:103], v[170:173], v[194:197], v[100:103]
	v_mfma_f32_16x16x32_bf16 v[92:95], v[178:181], v[194:197], v[92:95]
	v_mfma_f32_16x16x32_bf16 v[84:87], v[170:173], v[202:205], v[84:87]
	v_mfma_f32_16x16x32_bf16 v[76:79], v[178:181], v[202:205], v[76:79]
	v_mfma_f32_16x16x32_bf16 v[68:71], v[170:173], v[210:213], v[68:71]
	v_mfma_f32_16x16x32_bf16 v[64:67], v[178:181], v[210:213], v[64:67]
	s_setprio 0
	s_barrier
	s_add_i32 s36, s58, s5
	v_lshl_add_u64 v[144:145], v[144:145], 0, s[10:11]
	s_mov_b32 m0, s36
	ds_read_b128 v[182:185], v150 offset:49152
	ds_read_b128 v[186:189], v150 offset:50176
	ds_read_b128 v[190:193], v150 offset:51200
	ds_read_b128 v[194:197], v150 offset:52224
	ds_read_b128 v[198:201], v150 offset:53248
	ds_read_b128 v[202:205], v150 offset:54272
	ds_read_b128 v[206:209], v150 offset:55296
	ds_read_b128 v[210:213], v150 offset:56320
	global_load_lds_dwordx4 v[144:145], off
	s_add_i32 m0, s36, 0x2000
	s_add_u32 s34, s34, 0x80080
	v_lshl_add_u64 v[144:145], v[214:215], 0, s[10:11]
	s_addc_u32 s35, s35, 0
	s_add_i32 s36, s59, s5
	global_load_lds_dwordx4 v[144:145], off
	v_lshl_add_u64 v[144:145], s[34:35], 0, v[130:131]
	s_mov_b32 m0, s36
	s_nop 0
	global_load_lds_dwordx4 v[144:145], off
	v_lshl_add_u64 v[144:145], s[34:35], 0, v[134:135]
	s_add_i32 m0, s36, 0x2000
	s_nop 0
	global_load_lds_dwordx4 v[144:145], off
	s_waitcnt vmcnt(8)
	s_waitcnt lgkmcnt(0)
	s_barrier
	s_setprio 1
	s_waitcnt lgkmcnt(0)
	v_mfma_f32_16x16x32_bf16 v[60:63], v[140:143], v[182:185], v[60:63]
	v_mfma_f32_16x16x32_bf16 v[56:59], v[158:161], v[182:185], v[56:59]
	v_mfma_f32_16x16x32_bf16 v[48:51], v[140:143], v[190:193], v[48:51]
	v_mfma_f32_16x16x32_bf16 v[40:43], v[158:161], v[190:193], v[40:43]
	v_mfma_f32_16x16x32_bf16 v[32:35], v[140:143], v[198:201], v[32:35]
	v_mfma_f32_16x16x32_bf16 v[24:27], v[158:161], v[198:201], v[24:27]
	v_mfma_f32_16x16x32_bf16 v[16:19], v[140:143], v[206:209], v[16:19]
	v_mfma_f32_16x16x32_bf16 v[8:11], v[158:161], v[206:209], v[8:11]
	v_mfma_f32_16x16x32_bf16 v[60:63], v[154:157], v[186:189], v[60:63]
	v_mfma_f32_16x16x32_bf16 v[56:59], v[162:165], v[186:189], v[56:59]
	v_mfma_f32_16x16x32_bf16 v[48:51], v[154:157], v[194:197], v[48:51]
	v_mfma_f32_16x16x32_bf16 v[40:43], v[162:165], v[194:197], v[40:43]
	v_mfma_f32_16x16x32_bf16 v[32:35], v[154:157], v[202:205], v[32:35]
	v_mfma_f32_16x16x32_bf16 v[24:27], v[162:165], v[202:205], v[24:27]
	v_mfma_f32_16x16x32_bf16 v[16:19], v[154:157], v[210:213], v[16:19]
	v_mfma_f32_16x16x32_bf16 v[8:11], v[162:165], v[210:213], v[8:11]
	s_setprio 0
	s_setprio 1
	v_mfma_f32_16x16x32_bf16 v[52:55], v[166:169], v[182:185], v[52:55]
	v_mfma_f32_16x16x32_bf16 v[44:47], v[174:177], v[182:185], v[44:47]
	v_mfma_f32_16x16x32_bf16 v[36:39], v[166:169], v[190:193], v[36:39]
	v_mfma_f32_16x16x32_bf16 v[28:31], v[174:177], v[190:193], v[28:31]
	v_mfma_f32_16x16x32_bf16 v[20:23], v[166:169], v[198:201], v[20:23]
	v_mfma_f32_16x16x32_bf16 v[12:15], v[174:177], v[198:201], v[12:15]
	v_mfma_f32_16x16x32_bf16 v[4:7], v[166:169], v[206:209], v[4:7]
	v_mfma_f32_16x16x32_bf16 v[0:3], v[174:177], v[206:209], v[0:3]
	v_mfma_f32_16x16x32_bf16 v[52:55], v[170:173], v[186:189], v[52:55]
	v_mfma_f32_16x16x32_bf16 v[44:47], v[178:181], v[186:189], v[44:47]
	v_mfma_f32_16x16x32_bf16 v[36:39], v[170:173], v[194:197], v[36:39]
	v_mfma_f32_16x16x32_bf16 v[28:31], v[178:181], v[194:197], v[28:31]
	v_mfma_f32_16x16x32_bf16 v[20:23], v[170:173], v[202:205], v[20:23]
	v_mfma_f32_16x16x32_bf16 v[12:15], v[178:181], v[202:205], v[12:15]
	v_mfma_f32_16x16x32_bf16 v[4:7], v[170:173], v[210:213], v[4:7]
	v_mfma_f32_16x16x32_bf16 v[0:3], v[178:181], v[210:213], v[0:3]
	s_setprio 0
	s_waitcnt vmcnt(4)
	s_barrier
	s_add_i32 s72, s72, 2
	s_add_u32 s30, s30, 0x100
	s_addc_u32 s31, s31, 0
	s_add_u32 s70, s70, 0x100
	s_addc_u32 s71, s71, 0
	s_cmp_gt_u32 s72, 29
	s_cbranch_scc0 .LBB0_1324
	s_and_b64 vcc, exec, s[12:13]
	s_cbranch_vccz .LBB0_1327
	s_barrier

.LBB0_1393:
	v_add_u32_e32 v85, s4, v134
	s_nop 3
	ds_read_b128 v[224:227], v85
	ds_read_b128 v[228:231], v85 offset:4096
	ds_read_b128 v[232:235], v85 offset:8192
	ds_read_b128 v[236:239], v85 offset:12288
	ds_read_b128 v[240:243], v85 offset:16384
	ds_read_b128 v[244:247], v85 offset:20480
	ds_read_b128 v[248:251], v85 offset:24576
	ds_read_b128 v[92:95], v85 offset:28672
	s_addk_i32 s4, 0x200
	s_cmpk_lg_i32 s4, 0x800
	s_waitcnt lgkmcnt(0)
	v_mfma_f32_16x16x32_bf16 v[88:91], v[20:23], v[224:227], 0
	v_mfma_f32_16x16x32_bf16 v[88:91], v[24:27], v[228:231], v[88:91]
	v_mfma_f32_16x16x32_bf16 v[88:91], v[28:31], v[232:235], v[88:91]
	v_mfma_f32_16x16x32_bf16 v[88:91], v[32:35], v[236:239], v[88:91]
	v_mfma_f32_16x16x32_bf16 v[88:91], v[80:83], v[240:243], v[88:91]
	v_mfma_f32_16x16x32_bf16 v[88:91], v[36:39], v[244:247], v[88:91]
	v_mfma_f32_16x16x32_bf16 v[88:91], v[40:43], v[248:251], v[88:91]
	v_mfma_f32_16x16x32_bf16 v[88:91], v[60:63], v[92:95], v[88:91]
	s_nop 7
	ds_write_b128 v84, v[88:91]
	v_add_u32_e32 v84, 0x2100, v84
	s_cbranch_scc1 .LBB0_1393
	s_waitcnt lgkmcnt(0)
	s_barrier
	ds_read_b64 v[88:89], v114 offset:8192
	ds_read2st64_b32 v[84:85], v117 offset1:1
	ds_read2st64_b32 v[90:91], v118 offset1:1
	ds_read2st64_b32 v[92:93], v119 offset1:1
	ds_read2st64_b32 v[94:95], v120 offset1:1
	ds_read2st64_b32 v[96:97], v121 offset1:1
	ds_read2st64_b32 v[98:99], v122 offset1:1
	ds_read2st64_b32 v[100:101], v123 offset1:1
	ds_read2st64_b32 v[102:103], v124 offset1:1
	s_waitcnt lgkmcnt(8)
	v_pk_mul_f32 v[156:157], v[88:89], 0 op_sel_hi:[1,0]
	v_readlane_b32 s4, v252, 10
	v_sub_f32_e32 v110, v156, v157
	s_waitcnt lgkmcnt(7)
	v_add_f32_e32 v158, v84, v110
	v_add_f32_e32 v84, v156, v157
	v_add_f32_e32 v160, v85, v84
	v_pk_mul_f32 v[84:85], v[88:89], v[160:161] op_sel:[1,0] op_sel_hi:[0,0]
	v_pk_fma_f32 v[110:111], v[88:89], v[158:159], v[84:85] neg_lo:[0,0,1] neg_hi:[0,0,1]
	v_pk_fma_f32 v[84:85], v[88:89], v[158:159], v[84:85] op_sel_hi:[1,0,1]
	v_readlane_b32 s5, v252, 11
	v_mov_b32_e32 v111, v85
	s_waitcnt lgkmcnt(6)
	v_pk_add_f32 v[162:163], v[90:91], v[110:111]
	v_mov_b32_e32 v159, v135
	v_pk_mul_f32 v[84:85], v[88:89], v[162:163]
	s_nop 0
	v_sub_f32_e32 v84, v84, v85
	s_waitcnt lgkmcnt(5)
	v_add_f32_e32 v164, v92, v84
	v_pk_mul_f32 v[84:85], v[88:89], v[162:163] op_sel:[0,1] op_sel_hi:[1,0]
	s_nop 0
	v_add_f32_e32 v84, v84, v85
	v_add_f32_e32 v166, v93, v84
	v_pk_mul_f32 v[84:85], v[88:89], v[166:167] op_sel_hi:[1,0]
	s_nop 0
	v_pk_fma_f32 v[90:91], v[88:89], v[164:165], v[84:85] op_sel:[1,0,0] op_sel_hi:[0,1,1]
	v_pk_fma_f32 v[84:85], v[88:89], v[164:165], v[84:85] op_sel:[1,0,0] op_sel_hi:[0,0,1] neg_lo:[0,0,1] neg_hi:[0,0,1]
	v_mov_b32_e32 v91, v85
	s_waitcnt lgkmcnt(4)
	v_mov_b32_e32 v84, v95
	v_mov_b32_e32 v85, v94
	v_pk_add_f32 v[168:169], v[84:85], v[90:91]
	s_nop 0
	v_pk_mul_f32 v[84:85], v[88:89], v[168:169] op_sel:[0,1] op_sel_hi:[1,0]
	s_nop 0
	v_sub_f32_e32 v84, v84, v85
	s_waitcnt lgkmcnt(3)
	v_add_f32_e32 v170, v96, v84
	v_pk_mul_f32 v[84:85], v[88:89], v[168:169]
	s_nop 0
	v_add_f32_e32 v84, v84, v85
	v_add_f32_e32 v172, v97, v84
	v_pk_mul_f32 v[84:85], v[88:89], v[172:173] op_sel_hi:[1,0]
	s_nop 0
	v_pk_fma_f32 v[90:91], v[88:89], v[170:171], v[84:85] op_sel:[1,0,0] op_sel_hi:[0,1,1]
	v_pk_fma_f32 v[84:85], v[88:89], v[170:171], v[84:85] op_sel:[1,0,0] op_sel_hi:[0,0,1] neg_lo:[0,0,1] neg_hi:[0,0,1]
	v_mov_b32_e32 v91, v85
	s_waitcnt lgkmcnt(2)
	v_mov_b32_e32 v84, v99
	v_mov_b32_e32 v85, v98
	v_pk_add_f32 v[174:175], v[84:85], v[90:91]
	s_nop 0
	v_pk_mul_f32 v[84:85], v[88:89], v[174:175] op_sel:[0,1] op_sel_hi:[1,0]
	s_nop 0
	v_sub_f32_e32 v84, v84, v85
	s_waitcnt lgkmcnt(1)
	v_add_f32_e32 v100, v100, v84
	v_pk_mul_f32 v[84:85], v[88:89], v[174:175]
	s_nop 0
	v_add_f32_e32 v84, v84, v85
	v_add_f32_e32 v90, v101, v84
	v_pk_mul_f32 v[84:85], v[88:89], v[90:91] op_sel:[1,0] op_sel_hi:[0,0]
	v_pk_fma_f32 v[92:93], v[88:89], v[100:101], v[84:85] neg_lo:[0,0,1] neg_hi:[0,0,1]
	v_pk_fma_f32 v[84:85], v[88:89], v[100:101], v[84:85] op_sel_hi:[1,0,1]
	s_nop 0
	v_mov_b32_e32 v93, v85
	s_waitcnt lgkmcnt(0)
	v_pk_add_f32 v[84:85], v[102:103], v[92:93]
	ds_write_b64 v115, v[84:85]
	v_pk_mul_f32 v[84:85], v[88:89], v[88:89]
	s_waitcnt lgkmcnt(0)
	v_sub_f32_e32 v84, v84, v85
	v_add_f32_e32 v85, v88, v88
	v_mul_f32_e32 v85, v89, v85
	v_mul_f32_e32 v91, v84, v84
	v_add_f32_e32 v84, v84, v84
	v_mul_f32_e32 v84, v85, v84
	v_fma_f32 v91, -v85, v85, v91
	v_mul_f32_e32 v85, v84, v84
	s_barrier
	ds_read2st64_b64 v[92:95], v116 offset1:1
	ds_read2st64_b64 v[96:99], v116 offset0:2 offset1:3
	v_fma_f32 v110, v91, v91, -v85
	v_add_f32_e32 v85, v91, v91
	v_mul_f32_e32 v112, v84, v85
	v_mul_f32_e32 v85, v86, v112
	v_mul_f32_e32 v84, v87, v112
	v_fmac_f32_e32 v85, v87, v110
	v_fma_f32 v84, v86, v110, -v84
	s_waitcnt lgkmcnt(1)
	v_add_f32_e32 v85, v85, v93
	v_add_f32_e32 v84, v84, v92
	v_mul_f32_e32 v91, v112, v85
	v_cndmask_b32_e64 v86, v86, v84, s[4:5]
	v_fma_f32 v91, v110, v84, -v91
	v_mul_f32_e32 v84, v112, v84
	v_cndmask_b32_e64 v87, v87, v85, s[4:5]
	v_fmac_f32_e32 v84, v110, v85
	v_readlane_b32 s4, v252, 12
	v_add_f32_e32 v91, v94, v91
	v_add_f32_e32 v84, v95, v84
	v_readlane_b32 s5, v252, 13
	ds_read2st64_b64 v[92:95], v116 offset0:4 offset1:5
	v_mov_b32_e32 v113, v112
	v_cndmask_b32_e64 v85, v86, v91, s[4:5]
	v_cndmask_b32_e64 v86, v87, v84, s[4:5]
	v_mul_f32_e32 v87, v112, v84
	v_fma_f32 v87, v110, v91, -v87
	v_mul_f32_e32 v91, v112, v91
	v_fmac_f32_e32 v91, v110, v84
	s_waitcnt lgkmcnt(1)
	v_add_f32_e32 v84, v97, v91
	v_add_f32_e32 v87, v96, v87
	v_mul_f32_e32 v91, v112, v84
	v_cndmask_b32_e64 v85, v85, v87, s[6:7]
	v_fma_f32 v91, v110, v87, -v91
	v_mul_f32_e32 v87, v112, v87
	v_fmac_f32_e32 v87, v110, v84
	v_cndmask_b32_e64 v86, v86, v84, s[6:7]
	v_add_f32_e32 v91, v98, v91
	v_add_f32_e32 v84, v99, v87
	v_cndmask_b32_e64 v98, v85, v91, s[8:9]
	v_mul_f32_e32 v85, v112, v84
	v_mul_f32_e32 v97, v112, v91
	v_fma_f32 v96, v110, v91, -v85
	v_fmac_f32_e32 v97, v110, v84
	v_cndmask_b32_e64 v99, v86, v84, s[8:9]
	ds_read2st64_b64 v[84:87], v116 offset0:6 offset1:7
	s_waitcnt lgkmcnt(1)
	v_pk_add_f32 v[92:93], v[92:93], v[96:97]
	v_mov_b32_e32 v111, v110
	v_pk_mul_f32 v[96:97], v[112:113], v[92:93] op_sel_hi:[0,1]
	v_cndmask_b32_e64 v91, v98, v92, s[10:11]
	v_cndmask_b32_e64 v101, v99, v93, s[10:11]
	v_pk_fma_f32 v[98:99], v[110:111], v[92:93], v[96:97] op_sel:[0,0,1] op_sel_hi:[1,1,0] neg_lo:[0,0,1] neg_hi:[0,0,1]
	v_pk_fma_f32 v[92:93], v[110:111], v[92:93], v[96:97] op_sel:[0,0,1] op_sel_hi:[0,1,0]
	v_mov_b32_e32 v99, v93
	v_pk_add_f32 v[92:93], v[94:95], v[98:99]
	s_mov_b64 s[4:5], 0
	v_pk_mul_f32 v[94:95], v[112:113], v[92:93] op_sel_hi:[0,1]
	v_cndmask_b32_e64 v91, v91, v92, s[12:13]
	v_cndmask_b32_e64 v98, v101, v93, s[12:13]
	v_pk_fma_f32 v[96:97], v[110:111], v[92:93], v[94:95] op_sel:[0,0,1] op_sel_hi:[1,1,0] neg_lo:[0,0,1] neg_hi:[0,0,1]
	v_pk_fma_f32 v[92:93], v[110:111], v[92:93], v[94:95] op_sel:[0,0,1] op_sel_hi:[0,1,0]
	v_mov_b32_e32 v97, v93
	s_waitcnt lgkmcnt(0)
	v_pk_add_f32 v[84:85], v[84:85], v[96:97]
	s_nop 0
	v_cndmask_b32_e64 v91, v91, v84, s[14:15]
	v_cndmask_b32_e64 v92, v98, v85, s[14:15]
	v_add_f32_e32 v93, 0, v91
	v_fmac_f32_e32 v93, 0x80000000, v92
	v_add_f32_e32 v94, 0, v92
	v_bfe_u32 v95, v93, 16, 1
	v_fmac_f32_e32 v94, 0, v91
	v_add3_u32 v93, v93, v95, s1
	ds_write_b16_d16_hi v125, v93
	v_bfe_u32 v93, v94, 16, 1
	v_add3_u32 v93, v94, v93, s1
	ds_write_b16_d16_hi v125, v93 offset:128
	v_sub_f32_e32 v93, v88, v157
	v_add_f32_e32 v94, v89, v156
	v_fmac_f32_e32 v158, v93, v91
	v_fma_f32 v95, -v94, v92, v158
	v_fmac_f32_e32 v160, v93, v92
	v_bfe_u32 v96, v95, 16, 1
	v_fmac_f32_e32 v160, v94, v91
	v_add3_u32 v95, v95, v96, s1
	ds_write_b16_d16_hi v126, v95
	v_bfe_u32 v95, v160, 16, 1
	v_add3_u32 v95, v160, v95, s1
	ds_write_b16_d16_hi v126, v95 offset:128
	v_mul_f32_e32 v95, v88, v93
	v_fma_f32 v95, -v89, v94, v95
	v_mul_f32_e32 v93, v89, v93
	v_fmac_f32_e32 v93, v88, v94
	v_fma_f32 v94, v95, v91, v162
	v_fma_f32 v94, -v93, v92, v94
	v_fmac_f32_e32 v163, v95, v92
	v_bfe_u32 v96, v94, 16, 1
	v_fmac_f32_e32 v163, v93, v91
	v_add3_u32 v94, v94, v96, s1
	ds_write_b16_d16_hi v127, v94
	v_bfe_u32 v94, v163, 16, 1
	v_add3_u32 v94, v163, v94, s1
	ds_write_b16_d16_hi v127, v94 offset:128
	v_mul_f32_e32 v94, v88, v95
	v_fma_f32 v94, -v89, v93, v94
	v_mul_f32_e32 v95, v89, v95
	v_fmac_f32_e32 v95, v88, v93
	v_fmac_f32_e32 v164, v94, v91
	v_fma_f32 v93, -v95, v92, v164
	v_fmac_f32_e32 v166, v94, v92
	v_bfe_u32 v96, v93, 16, 1
	v_fmac_f32_e32 v166, v95, v91
	v_add3_u32 v93, v93, v96, s1
	ds_write_b16_d16_hi v128, v93
	v_bfe_u32 v93, v166, 16, 1
	v_add3_u32 v93, v166, v93, s1
	ds_write_b16_d16_hi v128, v93 offset:128
	v_mul_f32_e32 v93, v88, v94
	v_fma_f32 v93, -v89, v95, v93
	v_mul_f32_e32 v94, v89, v94
	v_fmac_f32_e32 v94, v88, v95
	v_fma_f32 v95, v93, v91, v169
	v_fma_f32 v95, -v94, v92, v95
	v_fmac_f32_e32 v168, v93, v92
	v_bfe_u32 v96, v95, 16, 1
	v_fmac_f32_e32 v168, v94, v91
	v_add3_u32 v95, v95, v96, s1
	ds_write_b16_d16_hi v129, v95
	v_bfe_u32 v95, v168, 16, 1
	v_add3_u32 v95, v168, v95, s1
	ds_write_b16_d16_hi v129, v95 offset:128
	v_mul_f32_e32 v95, v88, v93
	v_fma_f32 v95, -v89, v94, v95
	v_mul_f32_e32 v93, v89, v93
	v_fmac_f32_e32 v93, v88, v94
	v_fmac_f32_e32 v170, v95, v91
	v_fma_f32 v94, -v93, v92, v170
	v_fmac_f32_e32 v172, v95, v92
	v_bfe_u32 v96, v94, 16, 1
	v_fmac_f32_e32 v172, v93, v91
	v_add3_u32 v94, v94, v96, s1
	ds_write_b16_d16_hi v130, v94
	v_bfe_u32 v94, v172, 16, 1
	v_add3_u32 v94, v172, v94, s1
	ds_write_b16_d16_hi v130, v94 offset:128
	v_mul_f32_e32 v94, v88, v95
	v_fma_f32 v94, -v89, v93, v94
	v_mul_f32_e32 v95, v89, v95
	v_fmac_f32_e32 v95, v88, v93
	v_fma_f32 v93, v94, v91, v175
	v_fma_f32 v93, -v95, v92, v93
	v_fmac_f32_e32 v174, v94, v92
	v_bfe_u32 v96, v93, 16, 1
	v_fmac_f32_e32 v174, v95, v91
	v_add3_u32 v93, v93, v96, s1
	ds_write_b16_d16_hi v131, v93
	v_bfe_u32 v93, v174, 16, 1
	v_add3_u32 v93, v174, v93, s1
	ds_write_b16_d16_hi v131, v93 offset:128
	v_mul_f32_e32 v93, v88, v94
	v_fma_f32 v93, -v89, v95, v93
	v_mul_f32_e32 v89, v89, v94
	v_fmac_f32_e32 v89, v88, v95
	v_fmac_f32_e32 v100, v93, v91
	v_fma_f32 v88, -v89, v92, v100
	v_fmac_f32_e32 v90, v93, v92
	v_fmac_f32_e32 v90, v89, v91
	v_bfe_u32 v89, v88, 16, 1
	v_add3_u32 v88, v88, v89, s1
	ds_write_b16_d16_hi v132, v88
	v_bfe_u32 v88, v90, 16, 1
	v_add3_u32 v88, v90, v88, s1
	v_mov_b32_e32 v156, v138
	v_mov_b32_e32 v157, v137
	v_mov_b32_e32 v158, v136
	ds_write_b16_d16_hi v132, v88 offset:128
	s_waitcnt lgkmcnt(0)
	s_barrier
	v_mov_b32_e32 v176, 0
	v_mov_b32_e32 v177, 0
	v_mov_b32_e32 v178, 0
	v_mov_b32_e32 v179, 0
	s_and_saveexec_b64 s[54:55], s[16:17]
	ds_read_b128 v[176:179], v140 offset:25088
	s_or_b64 exec, exec, s[54:55]
	v_mov_b32_e32 v180, 0
	v_mov_b32_e32 v181, 0
	v_mov_b32_e32 v182, 0
	v_mov_b32_e32 v183, 0
	s_and_saveexec_b64 s[54:55], s[20:21]
	ds_read_b128 v[180:183], v142 offset:25088
	s_or_b64 exec, exec, s[54:55]
	v_mov_b32_e32 v184, 0
	v_mov_b32_e32 v185, 0
	v_mov_b32_e32 v186, 0
	v_mov_b32_e32 v187, 0
	s_and_saveexec_b64 s[54:55], s[24:25]
	ds_read_b128 v[184:187], v144 offset:25088
	s_or_b64 exec, exec, s[54:55]
	v_mov_b32_e32 v188, 0
	v_mov_b32_e32 v189, 0
	v_mov_b32_e32 v190, 0
	v_mov_b32_e32 v191, 0
	s_and_saveexec_b64 s[54:55], s[28:29]
	ds_read_b128 v[188:191], v146 offset:25088
	s_or_b64 exec, exec, s[54:55]
	v_mov_b32_e32 v192, 0
	v_mov_b32_e32 v193, 0
	v_mov_b32_e32 v194, 0
	v_mov_b32_e32 v195, 0
	s_and_saveexec_b64 s[54:55], s[18:19]
	ds_read_b128 v[192:195], v141 offset:25088
	s_or_b64 exec, exec, s[54:55]
	v_mov_b32_e32 v196, 0
	v_mov_b32_e32 v197, 0
	v_mov_b32_e32 v198, 0
	v_mov_b32_e32 v199, 0
	s_and_saveexec_b64 s[54:55], s[22:23]
	ds_read_b128 v[196:199], v143 offset:25088
	s_or_b64 exec, exec, s[54:55]
	v_mov_b32_e32 v200, 0
	v_mov_b32_e32 v201, 0
	v_mov_b32_e32 v202, 0
	v_mov_b32_e32 v203, 0
	s_and_saveexec_b64 s[54:55], s[26:27]
	ds_read_b128 v[200:203], v145 offset:25088
	s_or_b64 exec, exec, s[54:55]
	v_mov_b32_e32 v204, 0
	v_mov_b32_e32 v205, 0
	v_mov_b32_e32 v206, 0
	v_mov_b32_e32 v207, 0
	s_and_saveexec_b64 s[54:55], s[30:31]
	ds_read_b128 v[204:207], v147 offset:25088
	s_or_b64 exec, exec, s[54:55]
	v_mov_b32_e32 v208, 0
	v_mov_b32_e32 v209, 0
	v_mov_b32_e32 v210, 0
	v_mov_b32_e32 v211, 0
	s_and_saveexec_b64 s[54:55], s[36:37]
	ds_read_b128 v[208:211], v149 offset:25088
	s_or_b64 exec, exec, s[54:55]
	v_mov_b32_e32 v212, 0
	v_mov_b32_e32 v213, 0
	v_mov_b32_e32 v214, 0
	v_mov_b32_e32 v215, 0
	s_and_saveexec_b64 s[54:55], s[40:41]
	ds_read_b128 v[212:215], v151 offset:25088
	s_or_b64 exec, exec, s[54:55]
	v_mov_b32_e32 v216, 0
	v_mov_b32_e32 v217, 0
	v_mov_b32_e32 v218, 0
	v_mov_b32_e32 v219, 0
	s_and_saveexec_b64 s[54:55], s[44:45]
	ds_read_b128 v[216:219], v153 offset:25088
	s_or_b64 exec, exec, s[54:55]
	v_mov_b32_e32 v220, 0
	v_mov_b32_e32 v221, 0
	v_mov_b32_e32 v222, 0
	v_mov_b32_e32 v223, 0
	s_and_saveexec_b64 s[54:55], s[48:49]
	ds_read_b128 v[220:223], v155 offset:25088
	s_or_b64 exec, exec, s[54:55]
	s_waitcnt lgkmcnt(0)
	s_branch .LBB0_1397

.Ls5_epi:
	s_nop 2
	v_mov_b32_e32 v94, v162
	v_mov_b32_e32 v95, v163
	v_add_u32_e32 v158, 0x200, v158
	v_lshlrev_b32_e32 v92, 16, v94
	v_and_b32_e32 v93, 0xffff0000, v94
	v_pk_fma_f32 v[96:97], v[8:9], v[92:93], v[100:101]
	v_lshlrev_b32_e32 v94, 16, v95
	v_and_b32_e32 v93, 0x7fffffff, v97
	v_and_b32_e32 v92, 0x7fffffff, v96
	v_pk_fma_f32 v[92:93], v[92:93], s[80:81], 1.0 op_sel_hi:[1,0,0]
	v_and_b32_e32 v95, 0xffff0000, v95
	v_rcp_f32_e32 v98, v92
	v_rcp_f32_e32 v99, v93
	v_mov_b64_e32 v[92:93], s[54:55]
	v_cmp_gt_f32_e32 vcc, 0, v96
	v_pk_fma_f32 v[94:95], v[10:11], v[94:95], v[102:103]
	v_pk_fma_f32 v[100:101], v[98:99], s[50:51], v[92:93] op_sel_hi:[1,0,0]
	s_nop 0
	v_pk_fma_f32 v[100:101], v[98:99], v[100:101], s[76:77] op_sel_hi:[1,1,0]
	s_nop 0
	v_pk_fma_f32 v[100:101], v[98:99], v[100:101], s[78:79] op_sel_hi:[1,1,0]
	s_nop 0
	v_pk_fma_f32 v[100:101], v[98:99], v[100:101], s[2:3] op_sel_hi:[1,1,0]
	s_nop 0
	v_pk_mul_f32 v[98:99], v[98:99], v[100:101]
	v_pk_mul_f32 v[100:101], v[96:97], v[96:97]
	s_nop 0
	v_pk_mul_f32 v[100:101], v[100:101], s[0:1] op_sel_hi:[1,0]
	s_nop 0
	v_exp_f32_e32 v100, v100
	v_exp_f32_e32 v101, v101
	s_nop 0
	v_pk_mul_f32 v[98:99], v[100:101], v[98:99]
	s_nop 0
	v_pk_mul_f32 v[100:101], v[96:97], v[98:99]
	v_pk_fma_f32 v[98:99], v[96:97], v[98:99], v[96:97] neg_lo:[1,0,0] neg_hi:[1,0,0]
	v_and_b32_e32 v96, 0x7fffffff, v94
	v_cndmask_b32_e32 v100, v98, v100, vcc
	v_cmp_gt_f32_e32 vcc, 0, v97
	v_and_b32_e32 v97, 0x7fffffff, v95
	v_pk_fma_f32 v[96:97], v[96:97], s[80:81], 1.0 op_sel_hi:[1,0,0]
	v_cndmask_b32_e32 v101, v99, v101, vcc
	v_rcp_f32_e32 v96, v96
	v_rcp_f32_e32 v97, v97
	v_cmp_gt_f32_e32 vcc, 0, v94
	v_pk_fma_f32 v[98:99], v[96:97], s[50:51], v[92:93] op_sel_hi:[1,0,0]
	s_nop 0
	v_pk_fma_f32 v[98:99], v[96:97], v[98:99], s[76:77] op_sel_hi:[1,1,0]
	s_nop 0
	v_pk_fma_f32 v[98:99], v[96:97], v[98:99], s[78:79] op_sel_hi:[1,1,0]
	s_nop 0
	v_pk_fma_f32 v[98:99], v[96:97], v[98:99], s[2:3] op_sel_hi:[1,1,0]
	s_nop 0
	v_pk_mul_f32 v[96:97], v[96:97], v[98:99]
	v_pk_mul_f32 v[98:99], v[94:95], v[94:95]
	s_nop 0
	v_pk_mul_f32 v[98:99], v[98:99], s[0:1] op_sel_hi:[1,0]
	s_nop 0
	v_exp_f32_e32 v98, v98
	v_exp_f32_e32 v99, v99
	s_nop 0
	v_pk_mul_f32 v[96:97], v[98:99], v[96:97]
	s_nop 0
	v_pk_mul_f32 v[98:99], v[94:95], v[96:97]
	v_pk_fma_f32 v[96:97], v[94:95], v[96:97], v[94:95] neg_lo:[1,0,0] neg_hi:[1,0,0]
	v_cvt_pk_bf16_f32 v94, v100, v101
	s_nop 0
	v_cndmask_b32_e32 v96, v96, v98, vcc
	v_cmp_gt_f32_e32 vcc, 0, v95
	s_nop 1
	v_cndmask_b32_e32 v95, v97, v99, vcc
	v_cvt_pk_bf16_f32 v95, v96, v95
	v_lshl_add_u64 v[96:97], v[108:109], 0, s[4:5]
	global_store_dwordx2 v[96:97], v[94:95], off
	v_mov_b32_e32 v94, v168
	v_mov_b32_e32 v95, v169
	v_add_u32_e32 v159, 0x200, v159
	v_lshlrev_b32_e32 v96, 16, v94
	v_and_b32_e32 v97, 0xffff0000, v94
	v_pk_fma_f32 v[88:89], v[8:9], v[96:97], v[88:89]
	s_nop 0
	v_and_b32_e32 v97, 0x7fffffff, v89
	v_and_b32_e32 v96, 0x7fffffff, v88
	v_pk_fma_f32 v[96:97], v[96:97], s[80:81], 1.0 op_sel_hi:[1,0,0]
	v_cmp_gt_f32_e32 vcc, 0, v88
	v_rcp_f32_e32 v96, v96
	v_rcp_f32_e32 v97, v97
	s_nop 0
	v_pk_fma_f32 v[98:99], v[96:97], s[50:51], v[92:93] op_sel_hi:[1,0,0]
	s_nop 0
	v_pk_fma_f32 v[98:99], v[96:97], v[98:99], s[76:77] op_sel_hi:[1,1,0]
	s_nop 0
	v_pk_fma_f32 v[98:99], v[96:97], v[98:99], s[78:79] op_sel_hi:[1,1,0]
	s_nop 0
	v_pk_fma_f32 v[98:99], v[96:97], v[98:99], s[2:3] op_sel_hi:[1,1,0]
	s_nop 0
	v_pk_mul_f32 v[96:97], v[96:97], v[98:99]
	v_pk_mul_f32 v[98:99], v[88:89], v[88:89]
	s_nop 0
	v_pk_mul_f32 v[98:99], v[98:99], s[0:1] op_sel_hi:[1,0]
	s_nop 0
	v_exp_f32_e32 v98, v98
	v_exp_f32_e32 v99, v99
	s_nop 0
	v_pk_mul_f32 v[96:97], v[98:99], v[96:97]
	s_nop 0
	v_pk_mul_f32 v[98:99], v[88:89], v[96:97]
	v_pk_fma_f32 v[96:97], v[88:89], v[96:97], v[88:89] neg_lo:[1,0,0] neg_hi:[1,0,0]
	v_lshlrev_b32_e32 v88, 16, v95
	v_cndmask_b32_e32 v94, v96, v98, vcc
	v_cmp_gt_f32_e32 vcc, 0, v89
	v_and_b32_e32 v89, 0xffff0000, v95
	v_pk_fma_f32 v[88:89], v[10:11], v[88:89], v[90:91]
	v_cndmask_b32_e32 v96, v97, v99, vcc
	v_and_b32_e32 v91, 0x7fffffff, v89
	v_and_b32_e32 v90, 0x7fffffff, v88
	v_pk_fma_f32 v[90:91], v[90:91], s[80:81], 1.0 op_sel_hi:[1,0,0]
	v_cmp_gt_f32_e32 vcc, 0, v88
	v_rcp_f32_e32 v90, v90
	v_rcp_f32_e32 v91, v91
	s_nop 0
	v_pk_fma_f32 v[92:93], v[90:91], s[50:51], v[92:93] op_sel_hi:[1,0,0]
	s_nop 0
	v_pk_fma_f32 v[92:93], v[90:91], v[92:93], s[76:77] op_sel_hi:[1,1,0]
	s_nop 0
	v_pk_fma_f32 v[92:93], v[90:91], v[92:93], s[78:79] op_sel_hi:[1,1,0]
	s_nop 0
	v_pk_fma_f32 v[92:93], v[90:91], v[92:93], s[2:3] op_sel_hi:[1,1,0]
	s_nop 0
	v_pk_mul_f32 v[90:91], v[90:91], v[92:93]
	v_pk_mul_f32 v[92:93], v[88:89], v[88:89]
	s_nop 0
	v_pk_mul_f32 v[92:93], v[92:93], s[0:1] op_sel_hi:[1,0]
	s_nop 0
	v_exp_f32_e32 v92, v92
	v_exp_f32_e32 v93, v93
	s_nop 0
	v_pk_mul_f32 v[90:91], v[92:93], v[90:91]
	s_nop 0
	v_pk_mul_f32 v[92:93], v[88:89], v[90:91]
	v_pk_fma_f32 v[90:91], v[88:89], v[90:91], v[88:89] neg_lo:[1,0,0] neg_hi:[1,0,0]
	v_cvt_pk_bf16_f32 v88, v94, v96
	s_nop 0
	v_cndmask_b32_e32 v90, v90, v92, vcc
	v_cmp_gt_f32_e32 vcc, 0, v89
	s_nop 1
	v_cndmask_b32_e32 v89, v91, v93, vcc
	v_cvt_pk_bf16_f32 v89, v90, v89
	v_lshl_add_u64 v[90:91], v[106:107], 0, s[4:5]
	s_add_u32 s4, s4, 0x100000
	s_addc_u32 s5, s5, 0
	s_cmp_eq_u32 s4, 0x400000
	global_store_dwordx2 v[90:91], v[88:89], off
	s_cbranch_scc1 .LBB0_1391
.LBB0_1397:
	v_add_u32_e32 v160, 0, v156
	ds_read_b128 v[224:227], v160
	ds_read_b128 v[228:231], v160 offset:4096
	ds_read_b128 v[232:235], v160 offset:8192
	ds_read_b128 v[236:239], v160 offset:12288
	ds_read_b128 v[240:243], v160 offset:16384
	ds_read_b128 v[244:247], v160 offset:20480
	ds_read_b128 v[248:251], v160 offset:24576
	ds_read_b128 v[100:103], v160 offset:28672
	v_add_u32_e32 v160, 0x18600, v157
	ds_read_b128 v[96:99], v160
	ds_read_b64 v[162:163], v158
	ds_read_b64 v[168:169], v159
	s_mov_b32 s53, s52
	s_mov_b32 s55, s52
	s_mov_b32 s54, 0xbf3a00e3
	v_add_u32_e32 v156, 0x200, v156
	v_add_u32_e32 v157, 0x1100, v157
	s_waitcnt lgkmcnt(0)
	v_mfma_f32_16x16x32_bf16 v[88:91], v[176:179], v[224:227], 0
	v_mfma_f32_16x16x32_bf16 v[92:95], v[192:195], v[224:227], 0
	ds_read_b128 v[224:227], v160 offset:64
	v_mfma_f32_16x16x32_bf16 v[88:91], v[180:183], v[228:231], v[88:91]
	v_mfma_f32_16x16x32_bf16 v[92:95], v[196:199], v[228:231], v[92:95]
	ds_read_b128 v[228:231], v160 offset:128
	v_mfma_f32_16x16x32_bf16 v[88:91], v[184:187], v[232:235], v[88:91]
	v_mfma_f32_16x16x32_bf16 v[92:95], v[200:203], v[232:235], v[92:95]
	ds_read_b128 v[232:235], v160 offset:192
	v_mfma_f32_16x16x32_bf16 v[88:91], v[188:191], v[236:239], v[88:91]
	v_mfma_f32_16x16x32_bf16 v[92:95], v[204:207], v[236:239], v[92:95]
	v_mfma_f32_16x16x32_bf16 v[92:95], v[208:211], v[240:243], v[92:95]
	v_mfma_f32_16x16x32_bf16 v[92:95], v[212:215], v[244:247], v[92:95]
	v_mfma_f32_16x16x32_bf16 v[92:95], v[216:219], v[248:251], v[92:95]
	v_mfma_f32_16x16x32_bf16 v[92:95], v[220:223], v[100:103], v[92:95]
	s_waitcnt lgkmcnt(0)
	v_mfma_f32_16x16x32_bf16 v[88:91], v[44:47], v[96:99], v[88:91]
	v_mfma_f32_16x16x32_bf16 v[92:95], v[64:67], v[96:99], v[92:95]
	v_mfma_f32_16x16x32_bf16 v[88:91], v[48:51], v[224:227], v[88:91]
	v_mfma_f32_16x16x32_bf16 v[92:95], v[68:71], v[224:227], v[92:95]
	v_mfma_f32_16x16x32_bf16 v[88:91], v[52:55], v[228:231], v[88:91]
	v_mfma_f32_16x16x32_bf16 v[92:95], v[72:75], v[228:231], v[92:95]
	v_mfma_f32_16x16x32_bf16 v[100:103], v[56:59], v[232:235], v[88:91]
	v_mfma_f32_16x16x32_bf16 v[88:91], v[76:79], v[232:235], v[92:95]
	s_branch .Ls5_epi

.LBB0_1522:
	s_add_u32 s16, s94, 0xf200000
	s_addc_u32 s17, s95, 0
	s_add_u32 s18, s94, 0x12000000
	s_mov_b64 s[20:21], 0x80
	s_addc_u32 s19, s95, 0
	s_add_i32 m0, s7, 0x18000
	v_lshl_add_u64 v[6:7], v[6:7], 0, s[20:21]
	s_bfe_u32 s44, s33, 0x20006
	s_lshl_b32 s45, s2, 6
	s_waitcnt vmcnt(2)
	s_barrier
	global_load_lds_dwordx4 v[6:7], off
	v_lshl_add_u64 v[4:5], v[4:5], 0, s[20:21]
	s_add_i32 m0, s7, 0x1a000
	s_add_i32 s46, s7, 0x8000
	s_add_i32 s47, s7, 0xa000
	global_load_lds_dwordx4 v[4:5], off
	v_lshl_add_u64 v[0:1], v[0:1], 0, s[20:21]
	s_mov_b32 m0, s46
	s_add_u32 s0, s8, 0x80080
	global_load_lds_dwordx4 v[0:1], off
	v_lshl_add_u64 v[0:1], v[2:3], 0, s[20:21]
	s_mov_b32 m0, s47
	s_addc_u32 s1, s9, 0
	global_load_lds_dwordx4 v[0:1], off
	s_add_i32 m0, s7, 0x1c000
	v_lshl_add_u64 v[0:1], s[0:1], 0, v[146:147]
	global_load_lds_dwordx4 v[0:1], off
	v_lshl_add_u64 v[0:1], s[0:1], 0, v[144:145]
	s_add_i32 m0, s7, 0x1e000
	v_and_b32_e32 v182, 15, v8
	global_load_lds_dwordx4 v[0:1], off
	v_and_b32_e32 v0, 48, v8
	v_and_b32_e32 v1, 0xfffffc00, v12
	v_lshlrev_b32_e32 v3, 2, v8
	v_lshl_add_u32 v2, s2, 13, v1
	v_lshl_or_b32 v0, v182, 6, v0
	v_and_b32_e32 v3, 32, v3
	v_lshl_add_u32 v1, s44, 12, v1
	v_bitop3_b32 v2, v0, v2, v3 bitop3:0xde
	v_bitop3_b32 v184, v0, v1, v3 bitop3:0xde
	v_lshlrev_b32_e32 v0, 15, v13
	v_and_b32_e32 v0, 0xffff0000, v0
	v_lshl_add_u32 v0, v14, 12, v0
	v_and_b32_e32 v1, 1, v13
	v_lshl_or_b32 v0, v1, 6, v0
	v_lshl_add_u32 v148, v15, 1, v0
	v_lshlrev_b32_e32 v0, 15, v9
	s_cmpk_lt_u32 s33, 0x100
	v_and_b32_e32 v0, 0xffff0000, v0
	s_cselect_b64 s[24:25], -1, 0
	s_lshl_b32 s48, s44, 4
	v_lshl_add_u32 v0, v10, 12, v0
	v_and_b32_e32 v1, 1, v9
	s_waitcnt vmcnt(6)
	s_waitcnt lgkmcnt(0)
	s_add_u32 s26, s12, 0x2000
	v_lshl_or_b32 v0, v1, 6, v0
	s_addc_u32 s27, s13, 0
	v_lshl_add_u32 v150, v11, 1, v0
	s_add_i32 s49, 0, 0x10000
	s_add_i32 s50, 0, 0x14000
	v_mbcnt_lo_u32_b32 v0, -1, 0
	v_ashrrev_i32_e32 v183, 4, v8
	s_mov_b32 s23, 0
	v_mov_b32_e32 v149, v147
	v_mov_b32_e32 v151, v147
	v_add_u32_e32 v185, s49, v184
	v_add_u32_e32 v186, s50, v184
	v_add_u32_e32 v187, 0, v2
	v_mbcnt_hi_u32_b32 v188, -1, v0
	s_mov_b32 s51, 0
	s_barrier
	s_lshr_b32 s84, s88, 2
	s_mul_i32 s85, s84, 0x3000
	s_add_i32 s85, s85, s7
	s_mul_i32 s86, s84, 0x60000
	v_add_u32_e32 v222, s86, v148
	s_branch .LBB0_1525

.LBB0_1526:
	ds_read_b128 v[80:83], v185
	ds_read_b128 v[84:87], v185 offset:1024
	ds_read_b128 v[92:95], v185 offset:2048
	ds_read_b128 v[100:103], v185 offset:3072
	ds_read_b128 v[152:155], v186
	ds_read_b128 v[156:159], v186 offset:1024
	ds_read_b128 v[160:163], v186 offset:2048
	ds_read_b128 v[164:167], v186 offset:3072
	s_add_u32 s2, s0, 0xfff80080
	s_addc_u32 s3, s1, -1
	s_cmp_eq_u32 s58, 28
	s_cselect_b32 s31, s52, s3
	s_cselect_b32 s30, s53, s2
	s_cselect_b32 s3, s54, s57
	s_cselect_b32 s2, s55, s56
	s_sub_u32 s98, s0, 0x80000
	s_subb_u32 s99, s1, 0
	s_add_i32 m0, s85, 0x8000
	ds_read_b128 v[168:171], v187
	ds_read_b128 v[172:175], v187 offset:1024
	ds_read_b128 v[176:179], v187 offset:2048
	ds_read_b128 v[190:193], v187 offset:3072
	ds_read_b128 v[194:197], v187 offset:4096
	ds_read_b128 v[198:201], v187 offset:5120
	ds_read_b128 v[202:205], v187 offset:6144
	ds_read_b128 v[206:209], v187 offset:7168
	global_load_lds_dwordx4 v222, s[98:99]
	s_add_u32 s98, s98, 0x20000
	s_addc_u32 s99, s99, 0
	s_add_i32 m0, s85, 0x9000
	s_nop 0
	global_load_lds_dwordx4 v222, s[98:99]
	s_add_u32 s98, s98, 0x20000
	s_addc_u32 s99, s99, 0
	s_add_i32 m0, s85, 0xa000
	s_nop 0
	global_load_lds_dwordx4 v222, s[98:99]
	s_add_u32 s98, s98, 0x20000
	s_addc_u32 s99, s99, 0
	s_add_i32 m0, s85, 0xb000
	s_nop 0
	global_load_lds_dwordx4 v222, s[98:99]
	s_waitcnt vmcnt(8)
	s_waitcnt lgkmcnt(0)
	s_barrier
	s_setprio 1
	s_waitcnt lgkmcnt(0)
	v_mfma_f32_16x16x32_bf16 v[136:139], v[80:83], v[168:171], v[136:139]
	v_mfma_f32_16x16x32_bf16 v[140:143], v[92:95], v[168:171], v[140:143]
	v_mfma_f32_16x16x32_bf16 v[120:123], v[80:83], v[176:179], v[120:123]
	v_mfma_f32_16x16x32_bf16 v[124:127], v[92:95], v[176:179], v[124:127]
	v_mfma_f32_16x16x32_bf16 v[104:107], v[80:83], v[194:197], v[104:107]
	v_mfma_f32_16x16x32_bf16 v[108:111], v[92:95], v[194:197], v[108:111]
	v_mfma_f32_16x16x32_bf16 v[72:75], v[80:83], v[202:205], v[72:75]
	v_mfma_f32_16x16x32_bf16 v[76:79], v[92:95], v[202:205], v[76:79]
	v_mfma_f32_16x16x32_bf16 v[136:139], v[84:87], v[172:175], v[136:139]
	v_mfma_f32_16x16x32_bf16 v[140:143], v[100:103], v[172:175], v[140:143]
	v_mfma_f32_16x16x32_bf16 v[120:123], v[84:87], v[190:193], v[120:123]
	v_mfma_f32_16x16x32_bf16 v[124:127], v[100:103], v[190:193], v[124:127]
	v_mfma_f32_16x16x32_bf16 v[104:107], v[84:87], v[198:201], v[104:107]
	v_mfma_f32_16x16x32_bf16 v[108:111], v[100:103], v[198:201], v[108:111]
	v_mfma_f32_16x16x32_bf16 v[72:75], v[84:87], v[206:209], v[72:75]
	v_mfma_f32_16x16x32_bf16 v[76:79], v[100:103], v[206:209], v[76:79]
	s_setprio 0
	s_setprio 1
	v_mfma_f32_16x16x32_bf16 v[128:131], v[152:155], v[168:171], v[128:131]
	v_mfma_f32_16x16x32_bf16 v[132:135], v[160:163], v[168:171], v[132:135]
	v_mfma_f32_16x16x32_bf16 v[112:115], v[152:155], v[176:179], v[112:115]
	v_mfma_f32_16x16x32_bf16 v[116:119], v[160:163], v[176:179], v[116:119]
	v_mfma_f32_16x16x32_bf16 v[88:91], v[152:155], v[194:197], v[88:91]
	v_mfma_f32_16x16x32_bf16 v[96:99], v[160:163], v[194:197], v[96:99]
	v_mfma_f32_16x16x32_bf16 v[64:67], v[152:155], v[202:205], v[64:67]
	v_mfma_f32_16x16x32_bf16 v[68:71], v[160:163], v[202:205], v[68:71]
	v_mfma_f32_16x16x32_bf16 v[128:131], v[156:159], v[172:175], v[128:131]
	v_mfma_f32_16x16x32_bf16 v[132:135], v[164:167], v[172:175], v[132:135]
	v_mfma_f32_16x16x32_bf16 v[112:115], v[156:159], v[190:193], v[112:115]
	v_mfma_f32_16x16x32_bf16 v[116:119], v[164:167], v[190:193], v[116:119]
	v_mfma_f32_16x16x32_bf16 v[88:91], v[156:159], v[198:201], v[88:91]
	v_mfma_f32_16x16x32_bf16 v[96:99], v[164:167], v[198:201], v[96:99]
	v_mfma_f32_16x16x32_bf16 v[64:67], v[156:159], v[206:209], v[64:67]
	v_mfma_f32_16x16x32_bf16 v[68:71], v[164:167], v[206:209], v[68:71]
	s_setprio 0
	s_barrier
	s_add_i32 s59, s49, s39
	v_lshl_add_u64 v[180:181], s[2:3], 0, v[146:147]
	s_mov_b32 m0, s59
	ds_read_b128 v[168:171], v187 offset:16384
	ds_read_b128 v[172:175], v187 offset:17408
	ds_read_b128 v[176:179], v187 offset:18432
	ds_read_b128 v[190:193], v187 offset:19456
	ds_read_b128 v[194:197], v187 offset:20480
	ds_read_b128 v[198:201], v187 offset:21504
	ds_read_b128 v[202:205], v187 offset:22528
	ds_read_b128 v[206:209], v187 offset:23552
	global_load_lds_dwordx4 v[180:181], off
	s_add_i32 m0, s59, 0x2000
	s_add_u32 s60, s2, 0x80000
	v_lshl_add_u64 v[210:211], s[2:3], 0, v[144:145]
	s_addc_u32 s61, s3, 0
	s_add_i32 s59, s50, s39
	global_load_lds_dwordx4 v[210:211], off
	v_lshl_add_u64 v[212:213], s[60:61], 0, v[146:147]
	s_mov_b32 m0, s59
	global_load_lds_dwordx4 v[212:213], off
	v_lshl_add_u64 v[212:213], s[60:61], 0, v[144:145]
	s_add_i32 m0, s59, 0x2000
	s_nop 0
	global_load_lds_dwordx4 v[212:213], off
	s_waitcnt vmcnt(8)
	s_waitcnt lgkmcnt(0)
	s_barrier
	s_setprio 1
	s_waitcnt lgkmcnt(0)
	v_mfma_f32_16x16x32_bf16 v[56:59], v[80:83], v[168:171], v[56:59]
	v_mfma_f32_16x16x32_bf16 v[60:63], v[92:95], v[168:171], v[60:63]
	v_mfma_f32_16x16x32_bf16 v[40:43], v[80:83], v[176:179], v[40:43]
	v_mfma_f32_16x16x32_bf16 v[44:47], v[92:95], v[176:179], v[44:47]
	v_mfma_f32_16x16x32_bf16 v[24:27], v[80:83], v[194:197], v[24:27]
	v_mfma_f32_16x16x32_bf16 v[28:31], v[92:95], v[194:197], v[28:31]
	v_mfma_f32_16x16x32_bf16 v[8:11], v[80:83], v[202:205], v[8:11]
	v_mfma_f32_16x16x32_bf16 v[12:15], v[92:95], v[202:205], v[12:15]
	v_mfma_f32_16x16x32_bf16 v[56:59], v[84:87], v[172:175], v[56:59]
	v_mfma_f32_16x16x32_bf16 v[60:63], v[100:103], v[172:175], v[60:63]
	v_mfma_f32_16x16x32_bf16 v[40:43], v[84:87], v[190:193], v[40:43]
	v_mfma_f32_16x16x32_bf16 v[44:47], v[100:103], v[190:193], v[44:47]
	v_mfma_f32_16x16x32_bf16 v[24:27], v[84:87], v[198:201], v[24:27]
	v_mfma_f32_16x16x32_bf16 v[28:31], v[100:103], v[198:201], v[28:31]
	v_mfma_f32_16x16x32_bf16 v[8:11], v[84:87], v[206:209], v[8:11]
	v_mfma_f32_16x16x32_bf16 v[12:15], v[100:103], v[206:209], v[12:15]
	s_setprio 0
	s_setprio 1
	v_mfma_f32_16x16x32_bf16 v[48:51], v[152:155], v[168:171], v[48:51]
	v_mfma_f32_16x16x32_bf16 v[52:55], v[160:163], v[168:171], v[52:55]
	v_mfma_f32_16x16x32_bf16 v[32:35], v[152:155], v[176:179], v[32:35]
	v_mfma_f32_16x16x32_bf16 v[36:39], v[160:163], v[176:179], v[36:39]
	v_mfma_f32_16x16x32_bf16 v[16:19], v[152:155], v[194:197], v[16:19]
	v_mfma_f32_16x16x32_bf16 v[20:23], v[160:163], v[194:197], v[20:23]
	v_mfma_f32_16x16x32_bf16 v[0:3], v[152:155], v[202:205], v[0:3]
	v_mfma_f32_16x16x32_bf16 v[4:7], v[160:163], v[202:205], v[4:7]
	v_mfma_f32_16x16x32_bf16 v[48:51], v[156:159], v[172:175], v[48:51]
	v_mfma_f32_16x16x32_bf16 v[52:55], v[164:167], v[172:175], v[52:55]
	v_mfma_f32_16x16x32_bf16 v[32:35], v[156:159], v[190:193], v[32:35]
	v_mfma_f32_16x16x32_bf16 v[36:39], v[164:167], v[190:193], v[36:39]
	v_mfma_f32_16x16x32_bf16 v[16:19], v[156:159], v[198:201], v[16:19]
	v_mfma_f32_16x16x32_bf16 v[20:23], v[164:167], v[198:201], v[20:23]
	v_mfma_f32_16x16x32_bf16 v[0:3], v[156:159], v[206:209], v[0:3]
	v_mfma_f32_16x16x32_bf16 v[4:7], v[164:167], v[206:209], v[4:7]
	s_setprio 0
	s_waitcnt vmcnt(4)
	s_barrier
	s_add_i32 s59, 0, 0x18000
	s_add_i32 s60, 0, 0x1c000
	v_add_u32_e32 v100, s59, v184
	v_add_u32_e32 v164, s60, v184
	ds_read_b128 v[80:83], v100
	ds_read_b128 v[84:87], v100 offset:1024
	ds_read_b128 v[92:95], v100 offset:2048
	ds_read_b128 v[100:103], v100 offset:3072
	ds_read_b128 v[152:155], v164
	ds_read_b128 v[156:159], v164 offset:1024
	ds_read_b128 v[160:163], v164 offset:2048
	ds_read_b128 v[164:167], v164 offset:3072
	s_mov_b32 s98, s30
	s_mov_b32 s99, s31
	s_add_i32 m0, s85, 0
	ds_read_b128 v[168:171], v187 offset:32768
	ds_read_b128 v[172:175], v187 offset:33792
	ds_read_b128 v[176:179], v187 offset:34816
	ds_read_b128 v[190:193], v187 offset:35840
	ds_read_b128 v[194:197], v187 offset:36864
	ds_read_b128 v[198:201], v187 offset:37888
	ds_read_b128 v[202:205], v187 offset:38912
	ds_read_b128 v[206:209], v187 offset:39936
	global_load_lds_dwordx4 v222, s[98:99]
	s_add_u32 s98, s98, 0x20000
	s_addc_u32 s99, s99, 0
	s_add_i32 m0, s85, 0x1000
	s_nop 0
	global_load_lds_dwordx4 v222, s[98:99]
	s_add_u32 s98, s98, 0x20000
	s_addc_u32 s99, s99, 0
	s_add_i32 m0, s85, 0x2000
	s_nop 0
	global_load_lds_dwordx4 v222, s[98:99]
	s_add_u32 s98, s98, 0x20000
	s_addc_u32 s99, s99, 0
	s_add_i32 m0, s85, 0x3000
	s_nop 0
	global_load_lds_dwordx4 v222, s[98:99]
	s_waitcnt vmcnt(8)
	s_waitcnt lgkmcnt(0)
	s_barrier
	s_setprio 1
	s_waitcnt lgkmcnt(0)
	v_mfma_f32_16x16x32_bf16 v[136:139], v[80:83], v[168:171], v[136:139]
	v_mfma_f32_16x16x32_bf16 v[140:143], v[92:95], v[168:171], v[140:143]
	v_mfma_f32_16x16x32_bf16 v[120:123], v[80:83], v[176:179], v[120:123]
	v_mfma_f32_16x16x32_bf16 v[124:127], v[92:95], v[176:179], v[124:127]
	v_mfma_f32_16x16x32_bf16 v[104:107], v[80:83], v[194:197], v[104:107]
	v_mfma_f32_16x16x32_bf16 v[108:111], v[92:95], v[194:197], v[108:111]
	v_mfma_f32_16x16x32_bf16 v[72:75], v[80:83], v[202:205], v[72:75]
	v_mfma_f32_16x16x32_bf16 v[76:79], v[92:95], v[202:205], v[76:79]
	v_mfma_f32_16x16x32_bf16 v[136:139], v[84:87], v[172:175], v[136:139]
	v_mfma_f32_16x16x32_bf16 v[140:143], v[100:103], v[172:175], v[140:143]
	v_mfma_f32_16x16x32_bf16 v[120:123], v[84:87], v[190:193], v[120:123]
	v_mfma_f32_16x16x32_bf16 v[124:127], v[100:103], v[190:193], v[124:127]
	v_mfma_f32_16x16x32_bf16 v[104:107], v[84:87], v[198:201], v[104:107]
	v_mfma_f32_16x16x32_bf16 v[108:111], v[100:103], v[198:201], v[108:111]
	v_mfma_f32_16x16x32_bf16 v[72:75], v[84:87], v[206:209], v[72:75]
	v_mfma_f32_16x16x32_bf16 v[76:79], v[100:103], v[206:209], v[76:79]
	s_setprio 0
	s_setprio 1
	v_mfma_f32_16x16x32_bf16 v[128:131], v[152:155], v[168:171], v[128:131]
	v_mfma_f32_16x16x32_bf16 v[132:135], v[160:163], v[168:171], v[132:135]
	v_mfma_f32_16x16x32_bf16 v[112:115], v[152:155], v[176:179], v[112:115]
	v_mfma_f32_16x16x32_bf16 v[116:119], v[160:163], v[176:179], v[116:119]
	v_mfma_f32_16x16x32_bf16 v[88:91], v[152:155], v[194:197], v[88:91]
	v_mfma_f32_16x16x32_bf16 v[96:99], v[160:163], v[194:197], v[96:99]
	v_mfma_f32_16x16x32_bf16 v[64:67], v[152:155], v[202:205], v[64:67]
	v_mfma_f32_16x16x32_bf16 v[68:71], v[160:163], v[202:205], v[68:71]
	v_mfma_f32_16x16x32_bf16 v[128:131], v[156:159], v[172:175], v[128:131]
	v_mfma_f32_16x16x32_bf16 v[132:135], v[164:167], v[172:175], v[132:135]
	v_mfma_f32_16x16x32_bf16 v[112:115], v[156:159], v[190:193], v[112:115]
	v_mfma_f32_16x16x32_bf16 v[116:119], v[164:167], v[190:193], v[116:119]
	v_mfma_f32_16x16x32_bf16 v[88:91], v[156:159], v[198:201], v[88:91]
	v_mfma_f32_16x16x32_bf16 v[96:99], v[164:167], v[198:201], v[96:99]
	v_mfma_f32_16x16x32_bf16 v[64:67], v[156:159], v[206:209], v[64:67]
	v_mfma_f32_16x16x32_bf16 v[68:71], v[164:167], v[206:209], v[68:71]
	s_setprio 0
	s_barrier
	s_add_i32 s30, s59, s39
	v_lshl_add_u64 v[180:181], v[180:181], 0, s[20:21]
	s_mov_b32 m0, s30
	ds_read_b128 v[168:171], v187 offset:49152
	ds_read_b128 v[172:175], v187 offset:50176
	ds_read_b128 v[176:179], v187 offset:51200
	ds_read_b128 v[190:193], v187 offset:52224
	ds_read_b128 v[194:197], v187 offset:53248
	ds_read_b128 v[198:201], v187 offset:54272
	ds_read_b128 v[202:205], v187 offset:55296
	ds_read_b128 v[206:209], v187 offset:56320
	global_load_lds_dwordx4 v[180:181], off
	s_add_i32 m0, s30, 0x2000
	s_add_u32 s2, s2, 0x80080
	v_lshl_add_u64 v[180:181], v[210:211], 0, s[20:21]
	s_addc_u32 s3, s3, 0
	s_add_i32 s30, s60, s39
	global_load_lds_dwordx4 v[180:181], off
	v_lshl_add_u64 v[180:181], s[2:3], 0, v[146:147]
	s_mov_b32 m0, s30
	s_nop 0
	global_load_lds_dwordx4 v[180:181], off
	v_lshl_add_u64 v[180:181], s[2:3], 0, v[144:145]
	s_add_i32 m0, s30, 0x2000
	s_nop 0
	global_load_lds_dwordx4 v[180:181], off
	s_waitcnt vmcnt(8)
	s_waitcnt lgkmcnt(0)
	s_barrier
	s_setprio 1
	s_waitcnt lgkmcnt(0)
	v_mfma_f32_16x16x32_bf16 v[56:59], v[80:83], v[168:171], v[56:59]
	v_mfma_f32_16x16x32_bf16 v[60:63], v[92:95], v[168:171], v[60:63]
	v_mfma_f32_16x16x32_bf16 v[40:43], v[80:83], v[176:179], v[40:43]
	v_mfma_f32_16x16x32_bf16 v[44:47], v[92:95], v[176:179], v[44:47]
	v_mfma_f32_16x16x32_bf16 v[24:27], v[80:83], v[194:197], v[24:27]
	v_mfma_f32_16x16x32_bf16 v[28:31], v[92:95], v[194:197], v[28:31]
	v_mfma_f32_16x16x32_bf16 v[8:11], v[80:83], v[202:205], v[8:11]
	v_mfma_f32_16x16x32_bf16 v[12:15], v[92:95], v[202:205], v[12:15]
	v_mfma_f32_16x16x32_bf16 v[56:59], v[84:87], v[172:175], v[56:59]
	v_mfma_f32_16x16x32_bf16 v[60:63], v[100:103], v[172:175], v[60:63]
	v_mfma_f32_16x16x32_bf16 v[40:43], v[84:87], v[190:193], v[40:43]
	v_mfma_f32_16x16x32_bf16 v[44:47], v[100:103], v[190:193], v[44:47]
	v_mfma_f32_16x16x32_bf16 v[24:27], v[84:87], v[198:201], v[24:27]
	v_mfma_f32_16x16x32_bf16 v[28:31], v[100:103], v[198:201], v[28:31]
	v_mfma_f32_16x16x32_bf16 v[8:11], v[84:87], v[206:209], v[8:11]
	v_mfma_f32_16x16x32_bf16 v[12:15], v[100:103], v[206:209], v[12:15]
	s_setprio 0
	s_setprio 1
	v_mfma_f32_16x16x32_bf16 v[48:51], v[152:155], v[168:171], v[48:51]
	v_mfma_f32_16x16x32_bf16 v[52:55], v[160:163], v[168:171], v[52:55]
	v_mfma_f32_16x16x32_bf16 v[32:35], v[152:155], v[176:179], v[32:35]
	v_mfma_f32_16x16x32_bf16 v[36:39], v[160:163], v[176:179], v[36:39]
	v_mfma_f32_16x16x32_bf16 v[16:19], v[152:155], v[194:197], v[16:19]
	v_mfma_f32_16x16x32_bf16 v[20:23], v[160:163], v[194:197], v[20:23]
	v_mfma_f32_16x16x32_bf16 v[0:3], v[152:155], v[202:205], v[0:3]
	v_mfma_f32_16x16x32_bf16 v[4:7], v[160:163], v[202:205], v[4:7]
	v_mfma_f32_16x16x32_bf16 v[48:51], v[156:159], v[172:175], v[48:51]
	v_mfma_f32_16x16x32_bf16 v[52:55], v[164:167], v[172:175], v[52:55]
	v_mfma_f32_16x16x32_bf16 v[32:35], v[156:159], v[190:193], v[32:35]
	v_mfma_f32_16x16x32_bf16 v[36:39], v[164:167], v[190:193], v[36:39]
	v_mfma_f32_16x16x32_bf16 v[16:19], v[156:159], v[198:201], v[16:19]
	v_mfma_f32_16x16x32_bf16 v[20:23], v[164:167], v[198:201], v[20:23]
	v_mfma_f32_16x16x32_bf16 v[0:3], v[156:159], v[206:209], v[0:3]
	v_mfma_f32_16x16x32_bf16 v[4:7], v[164:167], v[206:209], v[4:7]
	s_setprio 0
	s_waitcnt vmcnt(4)
	s_barrier
	s_add_i32 s58, s58, 2
	s_add_u32 s0, s0, 0x100
	s_addc_u32 s1, s1, 0
	s_add_u32 s56, s56, 0x100
	s_addc_u32 s57, s57, 0
	s_cmp_gt_u32 s58, 29
	s_cbranch_scc0 .LBB0_1526
	s_and_b64 vcc, exec, s[24:25]
	s_cbranch_vccz .LBB0_1529
	s_barrier

.LBB0_1652:
	s_or_b64 exec, exec, s[14:15]
	s_mul_i32 s2, s16, 0x1400000
	s_add_u32 s2, s94, s2
	s_addc_u32 s3, s95, 0
	s_lshl_b32 s14, s16, 22
	s_sub_u32 s14, 0, s14
	s_subb_u32 s15, 0, 0
	s_add_u32 s2, s2, s14
	s_addc_u32 s3, s3, s15
	s_add_u32 s2, s2, 0x13c00000
	s_addc_u32 s3, s3, 0
	v_ashrrev_i32_e32 v0, 6, v24
	s_lshl_b32 s14, s17, 13
	v_lshl_add_u32 v2, v0, 10, s14
	s_lshl_b32 s14, s88, 5
	s_and_b32 s55, s14, 0x60
	v_and_b32_e32 v146, 15, v24
	v_and_b32_e32 v1, 48, v24
	v_lshlrev_b32_e32 v3, 2, v24
	s_lshr_b32 s14, s55, 3
	v_lshl_or_b32 v1, v146, 6, v1
	v_and_b32_e32 v3, 32, v3
	v_add_lshl_u32 v0, v0, s14, 10
	v_bitop3_b32 v2, v1, v2, v3 bitop3:0xde
	v_bitop3_b32 v0, v1, v0, v3 bitop3:0xde
	v_lshlrev_b32_e32 v1, 15, v26
	v_and_b32_e32 v1, 0xffff0000, v1
	v_lshl_add_u32 v1, v27, 12, v1
	v_and_b32_e32 v3, 1, v26
	v_lshl_or_b32 v1, v3, 6, v1
	s_lshl_b32 s54, s17, 6
	v_lshl_add_u32 v136, v28, 1, v1
	v_lshlrev_b32_e32 v1, 15, v29
	s_cmpk_lt_u32 s33, 0x100
	v_and_b32_e32 v1, 0xffff0000, v1
	s_cselect_b64 s[14:15], -1, 0
	s_lshl_b32 s16, s17, 8
	v_lshl_add_u32 v1, v30, 12, v1
	v_and_b32_e32 v3, 1, v29
	s_add_i32 s57, s16, 0
	v_mov_b32_e32 v137, 0
	v_lshl_or_b32 v1, v3, 6, v1
	s_add_i32 s59, 0, 0x10000
	s_add_i32 s60, 0, 0x14000
	s_add_i32 s61, 0, 0x18000
	s_add_i32 s62, 0, 0x1c000
	s_mov_b32 s53, 0
	v_ashrrev_i32_e32 v147, 4, v24
	s_mov_b32 s56, 0x20000
	s_add_i32 s57, s57, 0x20000
	v_lshl_add_u32 v138, v31, 1, v1
	v_mov_b32_e32 v139, v137
	s_mov_b32 s58, 0x10000
	v_add_u32_e32 v148, s59, v0
	v_add_u32_e32 v149, s60, v0
	v_add_u32_e32 v150, 0, v2
	s_mov_b64 s[16:17], 0x80000
	v_add_u32_e32 v151, s61, v0
	v_add_u32_e32 v152, s62, v0
	s_mov_b32 s18, 0x3d8293ee
	s_mov_b64 s[20:21], 0x10000
	s_mov_b64 s[22:23], 0x20000
	s_mov_b64 s[24:25], 0x30000
	s_mov_b32 s63, 0x30000
	s_mov_b32 s64, 0x80000
	s_mov_b64 s[26:27], 0x90000
	s_mov_b32 s65, 0x90000
	s_mov_b64 s[28:29], 0xa0000
	s_mov_b32 s66, 0xa0000
	s_mov_b64 s[30:31], 0xb0000
	s_mov_b32 s67, 0xb0000
	s_lshr_b32 s84, s88, 2
	s_mul_i32 s85, s84, 0x3000
	s_add_i32 s85, s85, s47
	s_mul_i32 s86, s84, 0x60000
	v_add_u32_e32 v222, s86, v136
	s_branch .LBB0_1655
